# baseline (speedup 1.0000x reference)
; #define PG8_STAGE(bufoff, gbase, voff) do { _Pragma("unroll") for (int _i = 0; _i < 2; ++_i) \
;         __builtin_amdgcn_global_load_lds((const unsigned*)((const char*)(gbase) + (voff)[_i]), (LAS unsigned*)(lds + (bufoff) + ldsw + _i * 8192), 16, 0, 0); } while (0)
; #define PG8_LDA(dst, b, h) do { _Pragma("unroll") for (int m = 0; m < 4; ++m) _Pragma("unroll") for (int k = 0; k < 2; ++k) dst[m][k] = *(const LAS bf16x8*)(lds + PG8_SA(b, h) + aoff + m * 2048 + k * 1024); } while (0)
; #define PG8_LDB(dst, b, h) do { _Pragma("unroll") for (int n = 0; n < 2; ++n) _Pragma("unroll") for (int k = 0; k < 2; ++k) dst[n][k] = *(const LAS bf16x8*)(lds + PG8_SB(b, h) + boff + n * 2048 + k * 1024); } while (0)
; #define PG8_MMA(ai, bj, At, Bt) do { __builtin_amdgcn_s_setprio(1); _Pragma("unroll") for (int m = 0; m < 4; ++m) _Pragma("unroll") for (int n = 0; n < 2; ++n) _Pragma("unroll") for (int k = 0; k < 2; ++k) \
;         acc[ai][bj][m][n] = __builtin_amdgcn_mfma_f32_16x16x32_bf16(Bt[n][k], At[m][k], acc[ai][bj][m][n], 0, 0, 0); __builtin_amdgcn_s_setprio(0); } while (0)
; #define PG8_WAIT_V(n) asm volatile("s_waitcnt vmcnt(" #n ")" ::: "memory")
; #define PG8_WAIT_L(n) asm volatile("s_waitcnt lgkmcnt(" #n ")" ::: "memory")
; template <class Epi, class Pre, bool AG = false>
; __device__ __forceinline__ void gemm_phase(LAS unsigned char* lds, const Gemm g, const StaticOrder& S, const Epi& E, const Pre& P) {
;     ...
;         for (int t = 0; t < nt; t += 2) {
;             const bool last = (t == nt - 2);
;             const char* a1 = cA + (size_t)(t + 1) * kstepA;
;             const char* a2 = last ? nA : cA + (size_t)(t + 2) * kstepA; const char* b2 = last ? nB : cB + (size_t)(t + 2) * kstep;
;             const char* a3 = a2 + kstepA; const char* b3 = b2 + kstep;
;             if constexpr (Epi::MIDK) { if (t == E.midk_t) E.mid(acc, cur, ui, wr, wc, fr, fq); }
;             PG8_LDB(B0, 0, 0); PG8_LDB(B1, 0, 1); PG8_SCHED; PG8_LDA(At, 0, 0); PG8_STAGE(PG8_SA(1, 1), a1 + hstepA, voffA);
;             PG8_WAIT_V(8); PG8_WAIT_L(0); PG8_BAR; PG8_MMA(0, 0, At, B0); PG8_MMA(0, 1, At, B1); PG8_BAR; PG8_SCHED;
;             PG8_LDA(At, 0, 1); PG8_STAGE(PG8_SB(0, 0), b2, voffB); PG8_STAGE(PG8_SB(0, 1), b2 + hstep, voffB); PG8_STAGE(PG8_SA(0, 0), a2, voffA);
;             PG8_WAIT_V(8); PG8_WAIT_L(0); PG8_BAR; PG8_MMA(1, 0, At, B0); PG8_MMA(1, 1, At, B1); PG8_BAR; PG8_SCHED;
.LBB0_479:
	s_add_u32 s14, s10, 0xfffc0080
	s_addc_u32 s21, s11, -1
	s_add_i32 vcc_lo, 0, 0x10000
	s_cmp_eq_u32 s87, 12
	s_cselect_b32 s57, s12, s21
	s_cselect_b32 s56, s13, s14
	s_cselect_b32 s55, s45, s86
	s_cselect_b32 s54, s71, s85
	s_add_i32 s14, 0, 0x14000
	v_add_u32_e32 v152, vcc_lo, v164
	v_add_u32_e32 v170, s14, v164
	ds_read_b128 v[130:133], v152
	ds_read_b128 v[134:137], v152 offset:1024
	ds_read_b128 v[148:151], v152 offset:2048
	ds_read_b128 v[152:155], v152 offset:3072
	ds_read_b128 v[156:159], v170
	ds_read_b128 v[160:163], v170 offset:1024
	ds_read_b128 v[166:169], v170 offset:2048
	ds_read_b128 v[170:173], v170 offset:3072
	v_lshl_add_u64 v[182:183], s[10:11], 0, v[0:1]
	s_add_i32 m0, s49, 0xc000
	ds_read_b128 v[174:177], v165
	ds_read_b128 v[178:181], v165 offset:1024
	ds_read_b128 v[188:191], v165 offset:2048
	ds_read_b128 v[194:197], v165 offset:3072
	ds_read_b128 v[198:201], v165 offset:4096
	ds_read_b128 v[202:205], v165 offset:5120
	ds_read_b128 v[206:209], v165 offset:6144
	ds_read_b128 v[210:213], v165 offset:7168
	global_load_lds_dwordx4 v[182:183], off
	v_lshl_add_u64 v[182:183], s[10:11], 0, v[146:147]
	s_add_i32 m0, s49, 0xe000
	s_nop 0
	global_load_lds_dwordx4 v[182:183], off
	s_waitcnt vmcnt(8)
	s_waitcnt lgkmcnt(0)
	s_barrier
	s_setprio 1
	s_waitcnt lgkmcnt(0)
	v_mfma_f32_16x16x32_bf16 v[126:129], v[130:133], v[174:177], v[126:129]
	v_mfma_f32_16x16x32_bf16 v[122:125], v[148:151], v[174:177], v[122:125]
	v_mfma_f32_16x16x32_bf16 v[110:113], v[130:133], v[188:191], v[110:113]
	v_mfma_f32_16x16x32_bf16 v[106:109], v[148:151], v[188:191], v[106:109]
	v_mfma_f32_16x16x32_bf16 v[94:97], v[130:133], v[198:201], v[94:97]
	v_mfma_f32_16x16x32_bf16 v[90:93], v[148:151], v[198:201], v[90:93]
	v_mfma_f32_16x16x32_bf16 v[78:81], v[130:133], v[206:209], v[78:81]
	v_mfma_f32_16x16x32_bf16 v[74:77], v[148:151], v[206:209], v[74:77]
	v_mfma_f32_16x16x32_bf16 v[126:129], v[134:137], v[178:181], v[126:129]
	v_mfma_f32_16x16x32_bf16 v[122:125], v[152:155], v[178:181], v[122:125]
	v_mfma_f32_16x16x32_bf16 v[110:113], v[134:137], v[194:197], v[110:113]
	v_mfma_f32_16x16x32_bf16 v[106:109], v[152:155], v[194:197], v[106:109]
	v_mfma_f32_16x16x32_bf16 v[94:97], v[134:137], v[202:205], v[94:97]
	v_mfma_f32_16x16x32_bf16 v[90:93], v[152:155], v[202:205], v[90:93]
	v_mfma_f32_16x16x32_bf16 v[78:81], v[134:137], v[210:213], v[78:81]
	v_mfma_f32_16x16x32_bf16 v[74:77], v[152:155], v[210:213], v[74:77]
	s_setprio 0
	s_setprio 1
	v_mfma_f32_16x16x32_bf16 v[118:121], v[156:159], v[174:177], v[118:121]
	v_mfma_f32_16x16x32_bf16 v[114:117], v[166:169], v[174:177], v[114:117]
	v_mfma_f32_16x16x32_bf16 v[102:105], v[156:159], v[188:191], v[102:105]
	v_mfma_f32_16x16x32_bf16 v[98:101], v[166:169], v[188:191], v[98:101]
	v_mfma_f32_16x16x32_bf16 v[86:89], v[156:159], v[198:201], v[86:89]
	v_mfma_f32_16x16x32_bf16 v[82:85], v[166:169], v[198:201], v[82:85]
	v_mfma_f32_16x16x32_bf16 v[70:73], v[156:159], v[206:209], v[70:73]
	v_mfma_f32_16x16x32_bf16 v[66:69], v[166:169], v[206:209], v[66:69]
	v_mfma_f32_16x16x32_bf16 v[118:121], v[160:163], v[178:181], v[118:121]
	v_mfma_f32_16x16x32_bf16 v[114:117], v[170:173], v[178:181], v[114:117]
	v_mfma_f32_16x16x32_bf16 v[102:105], v[160:163], v[194:197], v[102:105]
	v_mfma_f32_16x16x32_bf16 v[98:101], v[170:173], v[194:197], v[98:101]
	v_mfma_f32_16x16x32_bf16 v[86:89], v[160:163], v[202:205], v[86:89]
	v_mfma_f32_16x16x32_bf16 v[82:85], v[170:173], v[202:205], v[82:85]
	v_mfma_f32_16x16x32_bf16 v[70:73], v[160:163], v[210:213], v[70:73]
	v_mfma_f32_16x16x32_bf16 v[66:69], v[170:173], v[210:213], v[66:69]
	s_setprio 0
	s_barrier
	s_add_i32 s21, vcc_lo, s48
	v_lshl_add_u64 v[182:183], s[54:55], 0, v[142:143]
	s_mov_b32 m0, s21
	ds_read_b128 v[174:177], v165 offset:16384
	ds_read_b128 v[178:181], v165 offset:17408
	ds_read_b128 v[188:191], v165 offset:18432
	ds_read_b128 v[194:197], v165 offset:19456
	ds_read_b128 v[198:201], v165 offset:20480
	ds_read_b128 v[202:205], v165 offset:21504
	ds_read_b128 v[206:209], v165 offset:22528
	ds_read_b128 v[210:213], v165 offset:23552
	global_load_lds_dwordx4 v[182:183], off
	s_add_i32 m0, s21, 0x2000
	s_add_u32 vcc_lo, s54, 0x40000
	v_lshl_add_u64 v[184:185], s[54:55], 0, v[138:139]
	s_addc_u32 vcc_hi, s55, 0
	s_add_i32 s14, s14, s48
	global_load_lds_dwordx4 v[184:185], off
	v_lshl_add_u64 v[186:187], vcc, 0, v[142:143]
	s_mov_b32 m0, s14
	v_lshl_add_u64 v[192:193], s[56:57], 0, v[140:141]
	global_load_lds_dwordx4 v[186:187], off
	v_lshl_add_u64 v[186:187], vcc, 0, v[138:139]
	s_add_i32 m0, s14, 0x2000
	s_nop 0
	global_load_lds_dwordx4 v[186:187], off
	v_lshl_add_u64 v[186:187], s[56:57], 0, v[144:145]
	s_mov_b32 m0, s49
	s_nop 0
	global_load_lds_dwordx4 v[186:187], off
	s_mov_b32 m0, s38
	s_nop 0
	global_load_lds_dwordx4 v[192:193], off
	s_waitcnt vmcnt(8)
	s_waitcnt lgkmcnt(0)
	s_barrier
; #define PG8_STAGE(bufoff, gbase, voff) do { _Pragma("unroll") for (int _i = 0; _i < 2; ++_i) \
;         __builtin_amdgcn_global_load_lds((const unsigned*)((const char*)(gbase) + (voff)[_i]), (LAS unsigned*)(lds + (bufoff) + ldsw + _i * 8192), 16, 0, 0); } while (0)
; #define PG8_LDA(dst, b, h) do { _Pragma("unroll") for (int m = 0; m < 4; ++m) _Pragma("unroll") for (int k = 0; k < 2; ++k) dst[m][k] = *(const LAS bf16x8*)(lds + PG8_SA(b, h) + aoff + m * 2048 + k * 1024); } while (0)
; #define PG8_LDB(dst, b, h) do { _Pragma("unroll") for (int n = 0; n < 2; ++n) _Pragma("unroll") for (int k = 0; k < 2; ++k) dst[n][k] = *(const LAS bf16x8*)(lds + PG8_SB(b, h) + boff + n * 2048 + k * 1024); } while (0)
; #define PG8_MMA(ai, bj, At, Bt) do { __builtin_amdgcn_s_setprio(1); _Pragma("unroll") for (int m = 0; m < 4; ++m) _Pragma("unroll") for (int n = 0; n < 2; ++n) _Pragma("unroll") for (int k = 0; k < 2; ++k) \
;         acc[ai][bj][m][n] = __builtin_amdgcn_mfma_f32_16x16x32_bf16(Bt[n][k], At[m][k], acc[ai][bj][m][n], 0, 0, 0); __builtin_amdgcn_s_setprio(0); } while (0)
; #define PG8_WAIT_V(n) asm volatile("s_waitcnt vmcnt(" #n ")" ::: "memory")
; #define PG8_WAIT_L(n) asm volatile("s_waitcnt lgkmcnt(" #n ")" ::: "memory")
; #define PG8_BAR __builtin_amdgcn_s_barrier()
; #define PG8_SCHED __builtin_amdgcn_sched_barrier(0)
; template <class Epi, class Pre, bool AG = false>
; __device__ __forceinline__ void gemm_phase(LAS unsigned char* lds, const Gemm g, const StaticOrder& S, const Epi& E, const Pre& P) {
;     ...
;             PG8_WAIT_V(8); PG8_WAIT_L(0); PG8_BAR; PG8_MMA(1, 0, At, B0); PG8_MMA(1, 1, At, B1); PG8_BAR; PG8_SCHED;
;             PG8_LDB(B0, 1, 0); PG8_LDB(B1, 1, 1); PG8_SCHED; PG8_LDA(At, 1, 0); PG8_STAGE(PG8_SA(0, 1), a2 + hstepA, voffA);
;             PG8_WAIT_V(8); PG8_WAIT_L(0); PG8_BAR; PG8_MMA(0, 0, At, B0); PG8_MMA(0, 1, At, B1); PG8_BAR; PG8_SCHED;
	s_setprio 1
	s_waitcnt lgkmcnt(0)
	v_mfma_f32_16x16x32_bf16 v[62:65], v[130:133], v[174:177], v[62:65]
	v_mfma_f32_16x16x32_bf16 v[58:61], v[148:151], v[174:177], v[58:61]
	v_mfma_f32_16x16x32_bf16 v[46:49], v[130:133], v[188:191], v[46:49]
	v_mfma_f32_16x16x32_bf16 v[42:45], v[148:151], v[188:191], v[42:45]
	v_mfma_f32_16x16x32_bf16 v[30:33], v[130:133], v[198:201], v[30:33]
	v_mfma_f32_16x16x32_bf16 v[26:29], v[148:151], v[198:201], v[26:29]
	v_mfma_f32_16x16x32_bf16 v[14:17], v[130:133], v[206:209], v[14:17]
	v_mfma_f32_16x16x32_bf16 v[10:13], v[148:151], v[206:209], v[10:13]
	v_mfma_f32_16x16x32_bf16 v[62:65], v[134:137], v[178:181], v[62:65]
	v_mfma_f32_16x16x32_bf16 v[58:61], v[152:155], v[178:181], v[58:61]
	v_mfma_f32_16x16x32_bf16 v[46:49], v[134:137], v[194:197], v[46:49]
	v_mfma_f32_16x16x32_bf16 v[42:45], v[152:155], v[194:197], v[42:45]
	v_mfma_f32_16x16x32_bf16 v[30:33], v[134:137], v[202:205], v[30:33]
	v_mfma_f32_16x16x32_bf16 v[26:29], v[152:155], v[202:205], v[26:29]
	v_mfma_f32_16x16x32_bf16 v[14:17], v[134:137], v[210:213], v[14:17]
	v_mfma_f32_16x16x32_bf16 v[10:13], v[152:155], v[210:213], v[10:13]
	s_setprio 0
	s_setprio 1
	v_mfma_f32_16x16x32_bf16 v[54:57], v[156:159], v[174:177], v[54:57]
	v_mfma_f32_16x16x32_bf16 v[50:53], v[166:169], v[174:177], v[50:53]
	v_mfma_f32_16x16x32_bf16 v[38:41], v[156:159], v[188:191], v[38:41]
	v_mfma_f32_16x16x32_bf16 v[34:37], v[166:169], v[188:191], v[34:37]
	v_mfma_f32_16x16x32_bf16 v[22:25], v[156:159], v[198:201], v[22:25]
	v_mfma_f32_16x16x32_bf16 v[18:21], v[166:169], v[198:201], v[18:21]
	v_mfma_f32_16x16x32_bf16 v[6:9], v[156:159], v[206:209], v[6:9]
	v_mfma_f32_16x16x32_bf16 v[2:5], v[166:169], v[206:209], v[2:5]
	v_mfma_f32_16x16x32_bf16 v[54:57], v[160:163], v[178:181], v[54:57]
	v_mfma_f32_16x16x32_bf16 v[50:53], v[170:173], v[178:181], v[50:53]
	v_mfma_f32_16x16x32_bf16 v[38:41], v[160:163], v[194:197], v[38:41]
	v_mfma_f32_16x16x32_bf16 v[34:37], v[170:173], v[194:197], v[34:37]
	v_mfma_f32_16x16x32_bf16 v[22:25], v[160:163], v[202:205], v[22:25]
	v_mfma_f32_16x16x32_bf16 v[18:21], v[170:173], v[202:205], v[18:21]
	v_mfma_f32_16x16x32_bf16 v[6:9], v[160:163], v[210:213], v[6:9]
	v_mfma_f32_16x16x32_bf16 v[2:5], v[170:173], v[210:213], v[2:5]
	s_setprio 0
	s_barrier
	s_add_i32 s14, 0, 0x18000
	s_add_i32 s21, 0, 0x1c000
	v_add_u32_e32 v152, s14, v164
	v_add_u32_e32 v170, s21, v164
	ds_read_b128 v[130:133], v152
	ds_read_b128 v[134:137], v152 offset:1024
	ds_read_b128 v[148:151], v152 offset:2048
	ds_read_b128 v[152:155], v152 offset:3072
	ds_read_b128 v[156:159], v170
	ds_read_b128 v[160:163], v170 offset:1024
	ds_read_b128 v[166:169], v170 offset:2048
	ds_read_b128 v[170:173], v170 offset:3072
	s_add_u32 s56, s56, 0x40000
	s_addc_u32 s57, s57, 0
	s_mov_b32 m0, s58
	v_lshl_add_u64 v[214:215], s[56:57], 0, v[144:145]
	ds_read_b128 v[174:177], v165 offset:32768
	ds_read_b128 v[178:181], v165 offset:33792
	ds_read_b128 v[188:191], v165 offset:34816
	ds_read_b128 v[194:197], v165 offset:35840
	ds_read_b128 v[198:201], v165 offset:36864
	ds_read_b128 v[202:205], v165 offset:37888
	ds_read_b128 v[206:209], v165 offset:38912
	ds_read_b128 v[210:213], v165 offset:39936
	global_load_lds_dwordx4 v[214:215], off
	v_lshl_add_u64 v[214:215], s[56:57], 0, v[140:141]
	s_mov_b32 m0, s59
	s_nop 0
	global_load_lds_dwordx4 v[214:215], off
	s_waitcnt vmcnt(8)
	s_waitcnt lgkmcnt(0)
	s_barrier
	s_setprio 1
	s_waitcnt lgkmcnt(0)
	v_mfma_f32_16x16x32_bf16 v[126:129], v[130:133], v[174:177], v[126:129]
	v_mfma_f32_16x16x32_bf16 v[122:125], v[148:151], v[174:177], v[122:125]
	v_mfma_f32_16x16x32_bf16 v[110:113], v[130:133], v[188:191], v[110:113]
	v_mfma_f32_16x16x32_bf16 v[106:109], v[148:151], v[188:191], v[106:109]
	v_mfma_f32_16x16x32_bf16 v[94:97], v[130:133], v[198:201], v[94:97]
	v_mfma_f32_16x16x32_bf16 v[90:93], v[148:151], v[198:201], v[90:93]
	v_mfma_f32_16x16x32_bf16 v[78:81], v[130:133], v[206:209], v[78:81]
	v_mfma_f32_16x16x32_bf16 v[74:77], v[148:151], v[206:209], v[74:77]
	v_mfma_f32_16x16x32_bf16 v[126:129], v[134:137], v[178:181], v[126:129]
	v_mfma_f32_16x16x32_bf16 v[122:125], v[152:155], v[178:181], v[122:125]
	v_mfma_f32_16x16x32_bf16 v[110:113], v[134:137], v[194:197], v[110:113]
	v_mfma_f32_16x16x32_bf16 v[106:109], v[152:155], v[194:197], v[106:109]
	v_mfma_f32_16x16x32_bf16 v[94:97], v[134:137], v[202:205], v[94:97]
	v_mfma_f32_16x16x32_bf16 v[90:93], v[152:155], v[202:205], v[90:93]
	v_mfma_f32_16x16x32_bf16 v[78:81], v[134:137], v[210:213], v[78:81]
	v_mfma_f32_16x16x32_bf16 v[74:77], v[152:155], v[210:213], v[74:77]
	s_setprio 0
	s_setprio 1
	v_mfma_f32_16x16x32_bf16 v[118:121], v[156:159], v[174:177], v[118:121]
	v_mfma_f32_16x16x32_bf16 v[114:117], v[166:169], v[174:177], v[114:117]
	v_mfma_f32_16x16x32_bf16 v[102:105], v[156:159], v[188:191], v[102:105]
	v_mfma_f32_16x16x32_bf16 v[98:101], v[166:169], v[188:191], v[98:101]
	v_mfma_f32_16x16x32_bf16 v[86:89], v[156:159], v[198:201], v[86:89]
	v_mfma_f32_16x16x32_bf16 v[82:85], v[166:169], v[198:201], v[82:85]
	v_mfma_f32_16x16x32_bf16 v[70:73], v[156:159], v[206:209], v[70:73]
	v_mfma_f32_16x16x32_bf16 v[66:69], v[166:169], v[206:209], v[66:69]
	v_mfma_f32_16x16x32_bf16 v[118:121], v[160:163], v[178:181], v[118:121]
	v_mfma_f32_16x16x32_bf16 v[114:117], v[170:173], v[178:181], v[114:117]
	v_mfma_f32_16x16x32_bf16 v[102:105], v[160:163], v[194:197], v[102:105]
	v_mfma_f32_16x16x32_bf16 v[98:101], v[170:173], v[194:197], v[98:101]
	v_mfma_f32_16x16x32_bf16 v[86:89], v[160:163], v[202:205], v[86:89]
	v_mfma_f32_16x16x32_bf16 v[82:85], v[170:173], v[202:205], v[82:85]
	v_mfma_f32_16x16x32_bf16 v[70:73], v[160:163], v[210:213], v[70:73]
	v_mfma_f32_16x16x32_bf16 v[66:69], v[170:173], v[210:213], v[66:69]
	s_setprio 0
	s_barrier
; #define PG8_STAGE(bufoff, gbase, voff) do { _Pragma("unroll") for (int _i = 0; _i < 2; ++_i) \
;         __builtin_amdgcn_global_load_lds((const unsigned*)((const char*)(gbase) + (voff)[_i]), (LAS unsigned*)(lds + (bufoff) + ldsw + _i * 8192), 16, 0, 0); } while (0)
; #define PG8_LDA(dst, b, h) do { _Pragma("unroll") for (int m = 0; m < 4; ++m) _Pragma("unroll") for (int k = 0; k < 2; ++k) dst[m][k] = *(const LAS bf16x8*)(lds + PG8_SA(b, h) + aoff + m * 2048 + k * 1024); } while (0)
; #define PG8_MMA(ai, bj, At, Bt) do { __builtin_amdgcn_s_setprio(1); _Pragma("unroll") for (int m = 0; m < 4; ++m) _Pragma("unroll") for (int n = 0; n < 2; ++n) _Pragma("unroll") for (int k = 0; k < 2; ++k) \
;         acc[ai][bj][m][n] = __builtin_amdgcn_mfma_f32_16x16x32_bf16(Bt[n][k], At[m][k], acc[ai][bj][m][n], 0, 0, 0); __builtin_amdgcn_s_setprio(0); } while (0)
; template <class Epi, class Pre, bool AG = false>
; __device__ __forceinline__ void gemm_phase(LAS unsigned char* lds, const Gemm g, const StaticOrder& S, const Epi& E, const Pre& P) {
;     ...
;             PG8_WAIT_V(8); PG8_WAIT_L(0); PG8_BAR; PG8_MMA(0, 0, At, B0); PG8_MMA(0, 1, At, B1); PG8_BAR; PG8_SCHED;
;             PG8_LDA(At, 1, 1); PG8_STAGE(PG8_SB(1, 0), b3, voffB); PG8_STAGE(PG8_SB(1, 1), b3 + hstep, voffB); PG8_STAGE(PG8_SA(1, 0), a3, voffA);
;             PG8_WAIT_V(8); PG8_WAIT_L(0); PG8_BAR; PG8_MMA(1, 0, At, B0); PG8_MMA(1, 1, At, B1); PG8_BAR; PG8_SCHED;
;         }
;         if (wr == 0) PG8_BAR;
;         {
;             int te = threadIdx.x; asm volatile("" : "+v"(te));
;             const int le = te & 63;
;             E(acc, cur, ui, wr, wc, le & 15, le >> 4);
;     __device__ __forceinline__ void operator()(const AccT& acc, const pg8::Unit& u, int ui, int wr, int wc, int fr, int fq) const {
;         const int row0 = u.pm * 256 + wr * 64 + fr, col0 = u.pn * 256 + wc * 32 + 8 * fq;
;         float rs[2][4]; lane_rstd(lds, ui, wr, fr, rs);
; #pragma unroll
;         for (int ai = 0; ai < 2; ++ai)
; #pragma unroll
;         for (int mp = 0; mp < 2; ++mp) {
;             u32x4 hv[2][2], pv[2][2];
; #pragma unroll
;             for (int mm = 0; mm < 2; ++mm)
; #pragma unroll
;                 for (int bj = 0; bj < 2; ++bj) { const size_t o = (size_t)(row0 + ai * 128 + (2 * mp + mm) * 16) * D + col0 + 128 * bj; hv[mm][bj] = *(const u32x4*)(hin + o); pv[mm][bj] = *(const u32x4*)(pj + o); }
	s_add_i32 s14, s14, s48
	v_lshl_add_u64 v[182:183], v[182:183], 0, s[66:67]
	s_mov_b32 m0, s14
	ds_read_b128 v[174:177], v165 offset:49152
	ds_read_b128 v[178:181], v165 offset:50176
	ds_read_b128 v[188:191], v165 offset:51200
	ds_read_b128 v[194:197], v165 offset:52224
	ds_read_b128 v[198:201], v165 offset:53248
	ds_read_b128 v[202:205], v165 offset:54272
	ds_read_b128 v[206:209], v165 offset:55296
	ds_read_b128 v[210:213], v165 offset:56320
	global_load_lds_dwordx4 v[182:183], off
	s_add_i32 m0, s14, 0x2000
	s_add_u32 s54, s54, 0x40080
	v_lshl_add_u64 v[182:183], v[184:185], 0, s[66:67]
	s_addc_u32 s55, s55, 0
	s_add_i32 s14, s21, s48
	global_load_lds_dwordx4 v[182:183], off
	v_lshl_add_u64 v[182:183], s[54:55], 0, v[142:143]
	s_mov_b32 m0, s14
	s_nop 0
	global_load_lds_dwordx4 v[182:183], off
	v_lshl_add_u64 v[182:183], s[54:55], 0, v[138:139]
	s_add_i32 m0, s14, 0x2000
	s_nop 0
	global_load_lds_dwordx4 v[182:183], off
	v_lshl_add_u64 v[182:183], v[186:187], 0, s[66:67]
	s_mov_b32 m0, s53
	s_nop 0
	global_load_lds_dwordx4 v[182:183], off
	v_lshl_add_u64 v[182:183], v[192:193], 0, s[66:67]
	s_mov_b32 m0, s60
	s_nop 0
	global_load_lds_dwordx4 v[182:183], off
	s_waitcnt vmcnt(8)
	s_waitcnt lgkmcnt(0)
	s_barrier
	s_setprio 1
	s_waitcnt lgkmcnt(0)
	v_mfma_f32_16x16x32_bf16 v[62:65], v[130:133], v[174:177], v[62:65]
	v_mfma_f32_16x16x32_bf16 v[58:61], v[148:151], v[174:177], v[58:61]
	v_mfma_f32_16x16x32_bf16 v[46:49], v[130:133], v[188:191], v[46:49]
	v_mfma_f32_16x16x32_bf16 v[42:45], v[148:151], v[188:191], v[42:45]
	v_mfma_f32_16x16x32_bf16 v[30:33], v[130:133], v[198:201], v[30:33]
	v_mfma_f32_16x16x32_bf16 v[26:29], v[148:151], v[198:201], v[26:29]
	v_mfma_f32_16x16x32_bf16 v[14:17], v[130:133], v[206:209], v[14:17]
	v_mfma_f32_16x16x32_bf16 v[10:13], v[148:151], v[206:209], v[10:13]
	v_mfma_f32_16x16x32_bf16 v[62:65], v[134:137], v[178:181], v[62:65]
	v_mfma_f32_16x16x32_bf16 v[58:61], v[152:155], v[178:181], v[58:61]
	v_mfma_f32_16x16x32_bf16 v[46:49], v[134:137], v[194:197], v[46:49]
	v_mfma_f32_16x16x32_bf16 v[42:45], v[152:155], v[194:197], v[42:45]
	v_mfma_f32_16x16x32_bf16 v[30:33], v[134:137], v[202:205], v[30:33]
	v_mfma_f32_16x16x32_bf16 v[26:29], v[152:155], v[202:205], v[26:29]
	v_mfma_f32_16x16x32_bf16 v[14:17], v[134:137], v[210:213], v[14:17]
	v_mfma_f32_16x16x32_bf16 v[10:13], v[152:155], v[210:213], v[10:13]
	s_setprio 0
	s_setprio 1
	v_mfma_f32_16x16x32_bf16 v[54:57], v[156:159], v[174:177], v[54:57]
	v_mfma_f32_16x16x32_bf16 v[50:53], v[166:169], v[174:177], v[50:53]
	v_mfma_f32_16x16x32_bf16 v[38:41], v[156:159], v[188:191], v[38:41]
	v_mfma_f32_16x16x32_bf16 v[34:37], v[166:169], v[188:191], v[34:37]
	v_mfma_f32_16x16x32_bf16 v[22:25], v[156:159], v[198:201], v[22:25]
	v_mfma_f32_16x16x32_bf16 v[18:21], v[166:169], v[198:201], v[18:21]
	v_mfma_f32_16x16x32_bf16 v[6:9], v[156:159], v[206:209], v[6:9]
	v_mfma_f32_16x16x32_bf16 v[2:5], v[166:169], v[206:209], v[2:5]
	v_mfma_f32_16x16x32_bf16 v[54:57], v[160:163], v[178:181], v[54:57]
	v_mfma_f32_16x16x32_bf16 v[50:53], v[170:173], v[178:181], v[50:53]
	v_mfma_f32_16x16x32_bf16 v[38:41], v[160:163], v[194:197], v[38:41]
	v_mfma_f32_16x16x32_bf16 v[34:37], v[170:173], v[194:197], v[34:37]
	v_mfma_f32_16x16x32_bf16 v[22:25], v[160:163], v[202:205], v[22:25]
	v_mfma_f32_16x16x32_bf16 v[18:21], v[170:173], v[202:205], v[18:21]
	v_mfma_f32_16x16x32_bf16 v[6:9], v[160:163], v[210:213], v[6:9]
	v_mfma_f32_16x16x32_bf16 v[2:5], v[170:173], v[210:213], v[2:5]
	s_setprio 0
	s_barrier
	s_add_i32 s87, s87, 2
	s_add_u32 s10, s10, 0x100
	s_addc_u32 s11, s11, 0
	s_add_u32 s85, s85, 0x100
	s_addc_u32 s86, s86, 0
	s_cmp_gt_u32 s87, 13
	s_cbranch_scc0 .LBB0_479
	s_and_b64 vcc, exec, s[42:43]
	s_cbranch_vccz .LBB0_482
	s_barrier
.LBB0_482:
	s_mov_b32 s101, s62
	s_mov_b32 s99, 0
.Lfold_ple_again:
	v_mov_b32_e32 v130, v234
	s_lshl_b32 s10, s84, 8
	s_add_i32 s10, s10, s24
	v_and_b32_e32 v134, 15, v130
	v_or_b32_e32 v152, s10, v134
	s_lshl_b32 s10, s62, 8
	v_bfe_u32 v135, v130, 4, 2
	s_or_b32 s10, s10, s25
	v_lshl_or_b32 v148, v135, 3, s10
	v_ashrrev_i32_e32 v153, 31, v152
	v_ashrrev_i32_e32 v149, 31, v148
	v_lshlrev_b64 v[130:131], 10, v[152:153]
	v_lshl_add_u64 v[130:131], v[130:131], 0, v[148:149]
	v_lshlrev_b64 v[130:131], 1, v[130:131]
	v_lshl_add_u64 v[132:133], s[0:1], 0, v[130:131]
	global_load_dwordx4 v[166:169], v[132:133], off
	v_lshl_add_u64 v[132:133], s[28:29], 0, v[130:131]
	global_load_dwordx4 v[170:173], v[132:133], off
	s_lshl_b32 s10, s77, 10
	s_add_i32 s10, s61, s10
	v_or_b32_e32 v158, 16, v152
	v_lshl_add_u32 v132, v134, 2, s10
	v_ashrrev_i32_e32 v159, 31, v158
	ds_read2_b32 v[160:161], v132 offset1:16
	ds_read2_b32 v[156:157], v132 offset0:32 offset1:48
	ds_read2_b32 v[154:155], v132 offset0:128 offset1:144
	ds_read2_b32 v[150:151], v132 offset0:160 offset1:176
	v_lshlrev_b64 v[132:133], 10, v[158:159]
	v_or_b32_e32 v130, 0x100, v130
	v_cmp_eq_u32_e32 vcc, 0, v135
	v_lshl_add_u64 v[132:133], v[132:133], 0, v[148:149]
	v_lshl_add_u64 v[134:135], s[0:1], 0, v[130:131]
	v_lshlrev_b64 v[132:133], 1, v[132:133]
	global_load_dwordx4 v[174:177], v[134:135], off
	v_lshl_add_u64 v[130:131], s[28:29], 0, v[130:131]
	v_lshl_add_u64 v[136:137], s[0:1], 0, v[132:133]
	v_lshl_add_u64 v[182:183], s[28:29], 0, v[132:133]
	s_waitcnt lgkmcnt(0)
; __device__ __forceinline__ unsigned pk2(float lo, float hi) { unsigned r; asm("v_cvt_pk_bf16_f32 %0, %1, %2" : "=v"(r) : "v"(lo), "v"(hi)); return r; }
; __device__ __forceinline__ float bflo(unsigned w) { return __uint_as_float(w << 16); }
; __device__ __forceinline__ float bfhi(unsigned w) { return __uint_as_float(w & 0xffff0000u); }
; __device__ __forceinline__ float sigmoidf_(float x) { return __builtin_amdgcn_rcpf(1.0f + __expf(-x)); }
;     __device__ __forceinline__ void operator()(const AccT& acc, const pg8::Unit& u, int ui, int wr, int wc, int fr, int fq) const {
;     ...
;             for (int mm = 0; mm < 2; ++mm) {
;                 const int m = 2 * mp + mm; const int r = row0 + ai * 128 + m * 16; const float s = rs[ai][m]; float ss = 0.f;
; #pragma unroll
;                 for (int bj = 0; bj < 2; ++bj) {
;                     const u32x4 w0 = hv[mm][bj], pw = pv[mm][bj];
;                     f32x4 a = {bflo(w0.x), bfhi(w0.x), bflo(w0.y), bfhi(w0.y)}, b = {bflo(w0.z), bfhi(w0.z), bflo(w0.w), bfhi(w0.w)};
;                     const f32x4 g0 = acc[ai][bj][m][0] * s, g1 = acc[ai][bj][m][1] * s;
;                     a.x += bflo(pw.x) * sigmoidf_(g0.x); a.y += bfhi(pw.x) * sigmoidf_(g0.y); a.z += bflo(pw.y) * sigmoidf_(g0.z); a.w += bfhi(pw.y) * sigmoidf_(g0.w);
;                     b.x += bflo(pw.z) * sigmoidf_(g1.x); b.y += bfhi(pw.z) * sigmoidf_(g1.y); b.z += bflo(pw.w) * sigmoidf_(g1.z); b.w += bfhi(pw.w) * sigmoidf_(g1.w);
;                     ss += (a.x * a.x + a.y * a.y) + (a.z * a.z + a.w * a.w) + (b.x * b.x + b.y * b.y) + (b.z * b.z + b.w * b.w);
;                     u32x4 w; w.x = pk2(a.x, a.y); w.y = pk2(a.z, a.w); w.z = pk2(b.x, b.y); w.w = pk2(b.z, b.w); *(u32x4*)(hb_out + (size_t)r * D + col0 + 128 * bj) = w;
;                 }
;                 ss += __shfl_xor(ss, 16); ss += __shfl_xor(ss, 32); if (fq == 0) part_out[(size_t)r * 16 + u.pn * 4 + wc] = ss;
	v_pk_mul_f32 v[184:185], v[128:129], v[160:161] op_sel_hi:[1,0]
	v_pk_mul_f32 v[186:187], v[126:127], v[160:161] op_sel_hi:[1,0]
	global_load_dwordx4 v[178:181], v[130:131], off
	s_nop 0
	global_load_dwordx4 v[134:137], v[136:137], off
	s_nop 0
	global_load_dwordx4 v[126:129], v[182:183], off
	v_or_b32_e32 v132, 0x100, v132
	v_pk_mul_f32 v[188:189], v[124:125], v[160:161] op_sel_hi:[1,0]
	v_pk_mul_f32 v[122:123], v[122:123], v[160:161] op_sel_hi:[1,0]
	v_lshl_add_u64 v[124:125], s[0:1], 0, v[132:133]
	v_lshl_add_u64 v[182:183], s[28:29], 0, v[132:133]
	v_mul_f32_e32 v190, 0xbfb8aa3b, v122
	v_mul_f32_e32 v191, 0xbfb8aa3b, v123
	global_load_dwordx4 v[130:133], v[124:125], off
	s_nop 0
	global_load_dwordx4 v[122:125], v[182:183], off
	v_mul_f32_e32 v187, 0xbfb8aa3b, v187
	v_mul_f32_e32 v186, 0xbfb8aa3b, v186
	v_mul_f32_e32 v185, 0xbfb8aa3b, v185
	v_exp_f32_e32 v183, v187
	v_exp_f32_e32 v182, v186
	v_exp_f32_e32 v185, v185
	v_exp_f32_e32 v186, v190
	v_add_f32_e32 v183, 1.0, v183
	v_rcp_f32_e32 v183, v183
	v_add_f32_e32 v185, 1.0, v185
	v_add_f32_e32 v186, 1.0, v186
	v_exp_f32_e32 v187, v191
	v_add_f32_e32 v182, 1.0, v182
	v_rcp_f32_e32 v185, v185
	v_rcp_f32_e32 v186, v186
	v_rcp_f32_e32 v182, v182
	v_mul_f32_e32 v184, 0xbfb8aa3b, v184
	v_exp_f32_e32 v184, v184
	v_pk_mul_f32 v[118:119], v[118:119], v[160:161] op_sel_hi:[1,0]
	v_pk_mul_f32 v[120:121], v[120:121], v[160:161] op_sel_hi:[1,0]
	v_mul_f32_e32 v118, 0xbfb8aa3b, v118
	v_add_f32_e32 v184, 1.0, v184
	v_rcp_f32_e32 v184, v184
	v_exp_f32_e32 v118, v118
	v_mul_f32_e32 v119, 0xbfb8aa3b, v119
	v_exp_f32_e32 v119, v119
	v_pk_mul_f32 v[116:117], v[116:117], v[160:161] op_sel_hi:[1,0]
	v_add_f32_e32 v118, 1.0, v118
	v_rcp_f32_e32 v118, v118
	v_add_f32_e32 v119, 1.0, v119
	v_rcp_f32_e32 v119, v119
	v_pk_mul_f32 v[114:115], v[114:115], v[160:161] op_sel_hi:[1,0]
	v_mul_f32_e32 v116, 0xbfb8aa3b, v116
	v_mul_f32_e32 v114, 0xbfb8aa3b, v114
	v_exp_f32_e32 v114, v114
	v_mul_f32_e32 v115, 0xbfb8aa3b, v115
	v_exp_f32_e32 v115, v115
	v_exp_f32_e32 v116, v116
	v_add_f32_e32 v114, 1.0, v114
	v_rcp_f32_e32 v114, v114
	v_add_f32_e32 v115, 1.0, v115
	v_rcp_f32_e32 v115, v115
	v_mul_f32_e32 v117, 0xbfb8aa3b, v117
	v_exp_f32_e32 v117, v117
	v_lshlrev_b64 v[162:163], 11, v[152:153]
	s_lshl_b32 s54, s62, 2
	s_ashr_i32 s55, s54, 31
	s_waitcnt vmcnt(0)
	v_lshlrev_b32_e32 v190, 16, v166
	v_and_b32_e32 v166, 0xffff0000, v166
	v_lshlrev_b32_e32 v194, 16, v170
	v_and_b32_e32 v170, 0xffff0000, v170
	v_lshlrev_b32_e32 v191, 16, v167
	v_and_b32_e32 v167, 0xffff0000, v167
	v_lshlrev_b32_e32 v192, 16, v168
	v_lshlrev_b32_e32 v195, 16, v171
	v_and_b32_e32 v171, 0xffff0000, v171
	v_fmac_f32_e32 v166, v183, v170
	v_lshlrev_b32_e32 v170, 16, v172
	v_fmac_f32_e32 v167, v185, v171
	v_fmac_f32_e32 v192, v186, v170
	v_and_b32_e32 v170, 0xffff0000, v172
	v_add_f32_e32 v171, 1.0, v187
	v_mul_f32_e32 v172, 0xbfb8aa3b, v188
	v_fmac_f32_e32 v190, v182, v194
	v_rcp_f32_e32 v171, v171
	v_exp_f32_e32 v172, v172
	v_mul_f32_e32 v182, 0xbfb8aa3b, v189
	v_exp_f32_e32 v182, v182
	v_and_b32_e32 v168, 0xffff0000, v168
	v_fmac_f32_e32 v168, v171, v170
	v_add_f32_e32 v170, 1.0, v172
	v_rcp_f32_e32 v170, v170
	v_add_f32_e32 v171, 1.0, v182
	v_rcp_f32_e32 v171, v171
	v_lshlrev_b32_e32 v193, 16, v169
	v_lshlrev_b32_e32 v172, 16, v173
	v_and_b32_e32 v169, 0xffff0000, v169
	v_fmac_f32_e32 v193, v170, v172
	v_and_b32_e32 v170, 0xffff0000, v173
	v_fmac_f32_e32 v191, v184, v195
	v_fmac_f32_e32 v169, v171, v170
	v_mul_f32_e32 v170, v166, v166
	v_mul_f32_e32 v171, v167, v167
	v_fmac_f32_e32 v170, v190, v190
	v_fmac_f32_e32 v171, v191, v191
	v_add_f32_e32 v170, v170, v171
	v_mul_f32_e32 v171, v168, v168
	v_fmac_f32_e32 v171, v192, v192
	v_add_f32_e32 v170, v171, v170
	v_mul_f32_e32 v171, v169, v169
	v_fmac_f32_e32 v171, v193, v193
	v_add_f32_e32 v170, v171, v170
	v_lshlrev_b32_e32 v171, 16, v174
	v_lshlrev_b32_e32 v160, 16, v178
	v_and_b32_e32 v172, 0xffff0000, v174
	v_fmac_f32_e32 v171, v118, v160
	v_and_b32_e32 v118, 0xffff0000, v178
	v_fmac_f32_e32 v172, v119, v118
	v_mul_f32_e32 v118, 0xbfb8aa3b, v120
	v_exp_f32_e32 v118, v118
	v_mul_f32_e32 v119, 0xbfb8aa3b, v121
	v_exp_f32_e32 v119, v119
	v_lshlrev_b32_e32 v173, 16, v175
	v_add_f32_e32 v118, 1.0, v118
	v_rcp_f32_e32 v118, v118
	v_add_f32_e32 v119, 1.0, v119
	v_rcp_f32_e32 v119, v119
	v_lshlrev_b32_e32 v120, 16, v179
	v_and_b32_e32 v174, 0xffff0000, v175
	v_fmac_f32_e32 v173, v118, v120
	v_and_b32_e32 v118, 0xffff0000, v179
	v_lshlrev_b32_e32 v175, 16, v176
	v_fmac_f32_e32 v174, v119, v118
	v_lshlrev_b32_e32 v118, 16, v180
	v_and_b32_e32 v176, 0xffff0000, v176
	v_fmac_f32_e32 v175, v114, v118
	v_and_b32_e32 v114, 0xffff0000, v180
	v_fmac_f32_e32 v176, v115, v114
	v_add_f32_e32 v114, 1.0, v116
	v_rcp_f32_e32 v114, v114
	v_add_f32_e32 v115, 1.0, v117
	v_rcp_f32_e32 v115, v115
	v_lshlrev_b32_e32 v182, 16, v177
	v_lshlrev_b32_e32 v116, 16, v181
	v_and_b32_e32 v177, 0xffff0000, v177
	v_fmac_f32_e32 v182, v114, v116
	v_and_b32_e32 v114, 0xffff0000, v181
	v_fmac_f32_e32 v177, v115, v114
	v_mul_f32_e32 v114, v172, v172
	v_mul_f32_e32 v115, v174, v174
	v_fmac_f32_e32 v114, v171, v171
	v_fmac_f32_e32 v115, v173, v173
	v_add_f32_e32 v114, v114, v115
	v_mul_f32_e32 v115, v176, v176
	v_fmac_f32_e32 v115, v175, v175
	v_add_f32_e32 v114, v115, v114
	v_mul_f32_e32 v115, v177, v177
	v_fmac_f32_e32 v115, v182, v182
	v_add_f32_e32 v114, v115, v114
	v_and_b32_e32 v116, 64, v231
	v_add_f32_e32 v115, v170, v114
	v_xor_b32_e32 v114, 16, v231
	v_add_u32_e32 v119, 64, v116
	v_cmp_lt_i32_e64 s[10:11], v114, v119
	v_lshl_add_u64 v[116:117], s[26:27], 0, v[162:163]
	v_lshl_add_u64 v[162:163], v[148:149], 1, v[116:117]
	v_cndmask_b32_e64 v114, v231, v114, s[10:11]
	v_lshlrev_b32_e32 v114, 2, v114
	ds_bpermute_b32 v120, v114, v115
	v_cvt_pk_bf16_f32 v166, v190, v166
	v_cvt_pk_bf16_f32 v167, v191, v167
	v_cvt_pk_bf16_f32 v168, v192, v168
	v_cvt_pk_bf16_f32 v169, v193, v169
	s_waitcnt lgkmcnt(0)
	v_add_f32_e32 v116, v115, v120
	v_xor_b32_e32 v115, 32, v231
	v_cmp_lt_i32_e64 s[10:11], v115, v119
	global_store_dwordx4 v[162:163], v[166:169], off
	v_cvt_pk_bf16_f32 v118, v171, v172
	v_cvt_pk_bf16_f32 v119, v173, v174
	v_cvt_pk_bf16_f32 v120, v175, v176
	v_cvt_pk_bf16_f32 v121, v182, v177
	s_nop 0
	v_cndmask_b32_e64 v115, v231, v115, s[10:11]
	v_lshlrev_b32_e32 v115, 2, v115
	ds_bpermute_b32 v117, v115, v116
	global_store_dwordx4 v[162:163], v[118:121], off offset:256
	s_and_saveexec_b64 s[10:11], vcc
	s_cbranch_execz .LBB0_484
	v_lshlrev_b64 v[118:119], 6, v[152:153]
	v_lshl_add_u64 v[118:119], s[46:47], 0, v[118:119]
	v_lshl_add_u64 v[118:119], s[54:55], 2, v[118:119]
	s_lshl_b32 s62, s20, 2
	v_lshl_add_u64 v[118:119], v[118:119], 0, s[62:63]
	s_waitcnt lgkmcnt(0)
	v_add_f32_e32 v116, v116, v117
	global_store_dword v[118:119], v116, off

; __device__ __forceinline__ unsigned pk2(float lo, float hi) { unsigned r; asm("v_cvt_pk_bf16_f32 %0, %1, %2" : "=v"(r) : "v"(lo), "v"(hi)); return r; }
; __device__ __forceinline__ float bflo(unsigned w) { return __uint_as_float(w << 16); }
; __device__ __forceinline__ float bfhi(unsigned w) { return __uint_as_float(w & 0xffff0000u); }
;     __device__ __forceinline__ void operator()(const AccT& acc, const pg8::Unit& u, int ui, int wr, int wc, int fr, int fq) const {
;     ...
; #pragma unroll
;         for (int ai = 0; ai < 2; ++ai)
; #pragma unroll
;         for (int mp = 0; mp < 2; ++mp) {
;             u32x4 hv[2][2], pv[2][2];
; #pragma unroll
;             for (int mm = 0; mm < 2; ++mm)
; #pragma unroll
;                 for (int bj = 0; bj < 2; ++bj) { const size_t o = (size_t)(row0 + ai * 128 + (2 * mp + mm) * 16) * D + col0 + 128 * bj; hv[mm][bj] = *(const u32x4*)(hin + o); pv[mm][bj] = *(const u32x4*)(pj + o); }
; #pragma unroll
;             for (int mm = 0; mm < 2; ++mm) {
;                 const int m = 2 * mp + mm; const int r = row0 + ai * 128 + m * 16; const float s = rs[ai][m]; float ss = 0.f;
; #pragma unroll
;                 for (int bj = 0; bj < 2; ++bj) {
;                     const u32x4 w0 = hv[mm][bj], pw = pv[mm][bj];
;                     f32x4 a = {bflo(w0.x), bfhi(w0.x), bflo(w0.y), bfhi(w0.y)}, b = {bflo(w0.z), bfhi(w0.z), bflo(w0.w), bfhi(w0.w)};
;                     const f32x4 g0 = acc[ai][bj][m][0] * s, g1 = acc[ai][bj][m][1] * s;
;                     a.x += bflo(pw.x) * sigmoidf_(g0.x); a.y += bfhi(pw.x) * sigmoidf_(g0.y); a.z += bflo(pw.y) * sigmoidf_(g0.z); a.w += bfhi(pw.y) * sigmoidf_(g0.w);
;                     b.x += bflo(pw.z) * sigmoidf_(g1.x); b.y += bfhi(pw.z) * sigmoidf_(g1.y); b.z += bflo(pw.w) * sigmoidf_(g1.z); b.w += bfhi(pw.w) * sigmoidf_(g1.w);
;                     ss += (a.x * a.x + a.y * a.y) + (a.z * a.z + a.w * a.w) + (b.x * b.x + b.y * b.y) + (b.z * b.z + b.w * b.w);
;                     u32x4 w; w.x = pk2(a.x, a.y); w.y = pk2(a.z, a.w); w.z = pk2(b.x, b.y); w.w = pk2(b.z, b.w); *(u32x4*)(hb_out + (size_t)r * D + col0 + 128 * bj) = w;
;                 }
;                 ss += __shfl_xor(ss, 16); ss += __shfl_xor(ss, 32); if (fq == 0) part_out[(size_t)r * 16 + u.pn * 4 + wc] = ss;
;             }
;         }
.LBB0_490:
	s_or_b64 exec, exec, s[10:11]
	s_cmp_lg_u32 s99, 0
	s_cbranch_scc1 .Lfold_ple_done
	s_mov_b32 s99, 1
	s_mov_b32 s62, s101
	s_add_i32 s24, s24, 0x80
	s_add_i32 s61, s61, 0x200
	s_nop 1
	v_mov_b64_e32 v[126:127], v[62:63]
	v_mov_b64_e32 v[128:129], v[64:65]
	v_mov_b64_e32 v[122:123], v[58:59]
	v_mov_b64_e32 v[124:125], v[60:61]
	v_mov_b64_e32 v[110:111], v[46:47]
	v_mov_b64_e32 v[112:113], v[48:49]
	v_mov_b64_e32 v[106:107], v[42:43]
	v_mov_b64_e32 v[108:109], v[44:45]
	v_mov_b64_e32 v[94:95], v[30:31]
	v_mov_b64_e32 v[96:97], v[32:33]
	v_mov_b64_e32 v[90:91], v[26:27]
	v_mov_b64_e32 v[92:93], v[28:29]
	v_mov_b64_e32 v[78:79], v[14:15]
	v_mov_b64_e32 v[80:81], v[16:17]
	v_mov_b64_e32 v[74:75], v[10:11]
	v_mov_b64_e32 v[76:77], v[12:13]
	v_mov_b64_e32 v[118:119], v[54:55]
	v_mov_b64_e32 v[120:121], v[56:57]
	v_mov_b64_e32 v[114:115], v[50:51]
	v_mov_b64_e32 v[116:117], v[52:53]
	v_mov_b64_e32 v[102:103], v[38:39]
	v_mov_b64_e32 v[104:105], v[40:41]
	v_mov_b64_e32 v[98:99], v[34:35]
	v_mov_b64_e32 v[100:101], v[36:37]
	v_mov_b64_e32 v[86:87], v[22:23]
	v_mov_b64_e32 v[88:89], v[24:25]
	v_mov_b64_e32 v[82:83], v[18:19]
	v_mov_b64_e32 v[84:85], v[20:21]
	v_mov_b64_e32 v[70:71], v[6:7]
	v_mov_b64_e32 v[72:73], v[8:9]
	v_mov_b64_e32 v[66:67], v[2:3]
	v_mov_b64_e32 v[68:69], v[4:5]
	s_branch .Lfold_ple_again
.Lfold_ple_done:
	s_sub_i32 s24, s24, 0x80
	s_sub_i32 s61, s61, 0x200

; #define PG8_STAGE(bufoff, gbase, voff) do { _Pragma("unroll") for (int _i = 0; _i < 2; ++_i) \
;         __builtin_amdgcn_global_load_lds((const unsigned*)((const char*)(gbase) + (voff)[_i]), (LAS unsigned*)(lds + (bufoff) + ldsw + _i * 8192), 16, 0, 0); } while (0)
; #define PG8_LDA(dst, b, h) do { _Pragma("unroll") for (int m = 0; m < 4; ++m) _Pragma("unroll") for (int k = 0; k < 2; ++k) dst[m][k] = *(const LAS bf16x8*)(lds + PG8_SA(b, h) + aoff + m * 2048 + k * 1024); } while (0)
; #define PG8_LDB(dst, b, h) do { _Pragma("unroll") for (int n = 0; n < 2; ++n) _Pragma("unroll") for (int k = 0; k < 2; ++k) dst[n][k] = *(const LAS bf16x8*)(lds + PG8_SB(b, h) + boff + n * 2048 + k * 1024); } while (0)
; #define PG8_MMA(ai, bj, At, Bt) do { __builtin_amdgcn_s_setprio(1); _Pragma("unroll") for (int m = 0; m < 4; ++m) _Pragma("unroll") for (int n = 0; n < 2; ++n) _Pragma("unroll") for (int k = 0; k < 2; ++k) \
;         acc[ai][bj][m][n] = __builtin_amdgcn_mfma_f32_16x16x32_bf16(Bt[n][k], At[m][k], acc[ai][bj][m][n], 0, 0, 0); __builtin_amdgcn_s_setprio(0); } while (0)
; #define PG8_WAIT_V(n) asm volatile("s_waitcnt vmcnt(" #n ")" ::: "memory")
; #define PG8_WAIT_L(n) asm volatile("s_waitcnt lgkmcnt(" #n ")" ::: "memory")
; template <class Epi, class Pre, bool AG = false>
; __device__ __forceinline__ void gemm_phase(LAS unsigned char* lds, const Gemm g, const StaticOrder& S, const Epi& E, const Pre& P) {
;     ...
;         for (int t = 0; t < nt; t += 2) {
;             const bool last = (t == nt - 2);
;             const char* a1 = cA + (size_t)(t + 1) * kstepA;
;             const char* a2 = last ? nA : cA + (size_t)(t + 2) * kstepA; const char* b2 = last ? nB : cB + (size_t)(t + 2) * kstep;
;             const char* a3 = a2 + kstepA; const char* b3 = b2 + kstep;
;             if constexpr (Epi::MIDK) { if (t == E.midk_t) E.mid(acc, cur, ui, wr, wc, fr, fq); }
;             PG8_LDB(B0, 0, 0); PG8_LDB(B1, 0, 1); PG8_SCHED; PG8_LDA(At, 0, 0); PG8_STAGE(PG8_SA(1, 1), a1 + hstepA, voffA);
;             PG8_WAIT_V(8); PG8_WAIT_L(0); PG8_BAR; PG8_MMA(0, 0, At, B0); PG8_MMA(0, 1, At, B1); PG8_BAR; PG8_SCHED;
;             PG8_LDA(At, 0, 1); PG8_STAGE(PG8_SB(0, 0), b2, voffB); PG8_STAGE(PG8_SB(0, 1), b2 + hstep, voffB); PG8_STAGE(PG8_SA(0, 0), a2, voffA);
;             PG8_WAIT_V(8); PG8_WAIT_L(0); PG8_BAR; PG8_MMA(1, 0, At, B0); PG8_MMA(1, 1, At, B1); PG8_BAR; PG8_SCHED;
.LBB0_741:
	s_add_u32 s54, s10, 0x400000
	s_addc_u32 s55, s11, 0
	s_cmp_eq_u32 s87, 4
	s_cselect_b32 s60, s13, s54
	s_cselect_b32 s61, s12, s55
	s_cselect_b32 s58, s29, vcc_lo
	s_cselect_b32 s59, s27, vcc_hi
	s_add_u32 s56, s60, 0x200000
	s_addc_u32 s57, s61, 0
	s_add_i32 s21, 0, 0x10000
	v_add_u32_e32 v0, s21, v238
	s_add_i32 s14, 0, 0x14000
	ds_read_b128 v[58:61], v0
	ds_read_b128 v[62:65], v0 offset:1024
	ds_read_b128 v[74:77], v0 offset:2048
	ds_read_b128 v[78:81], v0 offset:3072
	v_add_u32_e32 v0, s14, v238
	ds_read_b128 v[138:141], v0
	ds_read_b128 v[142:145], v0 offset:1024
	ds_read_b128 v[146:149], v0 offset:2048
	ds_read_b128 v[150:153], v0 offset:3072
	v_lshl_add_u64 v[178:179], s[10:11], 0, v[202:203]
	s_add_i32 m0, s49, 0xc000
	ds_read_b128 v[154:157], v239
	ds_read_b128 v[166:169], v239 offset:1024
	ds_read_b128 v[170:173], v239 offset:2048
	ds_read_b128 v[174:177], v239 offset:3072
	ds_read_b128 v[206:209], v239 offset:4096
	ds_read_b128 v[210:213], v239 offset:5120
	ds_read_b128 v[214:217], v239 offset:6144
	ds_read_b128 v[218:221], v239 offset:7168
	global_load_lds_dwordx4 v[178:179], off
	v_lshl_add_u64 v[178:179], s[10:11], 0, v[204:205]
	s_add_i32 m0, s49, 0xe000
	s_nop 0
	global_load_lds_dwordx4 v[178:179], off
	s_waitcnt vmcnt(8)
	s_waitcnt lgkmcnt(0)
	s_barrier
	s_setprio 1
	s_waitcnt lgkmcnt(0)
	v_mfma_f32_16x16x32_bf16 v[162:165], v[58:61], v[154:157], v[162:165]
	v_mfma_f32_16x16x32_bf16 v[158:161], v[74:77], v[154:157], v[158:161]
	v_mfma_f32_16x16x32_bf16 v[126:129], v[58:61], v[170:173], v[126:129]
	v_mfma_f32_16x16x32_bf16 v[122:125], v[74:77], v[170:173], v[122:125]
	v_mfma_f32_16x16x32_bf16 v[110:113], v[58:61], v[206:209], v[110:113]
	v_mfma_f32_16x16x32_bf16 v[106:109], v[74:77], v[206:209], v[106:109]
	v_mfma_f32_16x16x32_bf16 v[94:97], v[58:61], v[214:217], v[94:97]
	v_mfma_f32_16x16x32_bf16 v[90:93], v[74:77], v[214:217], v[90:93]
	v_mfma_f32_16x16x32_bf16 v[162:165], v[62:65], v[166:169], v[162:165]
	v_mfma_f32_16x16x32_bf16 v[158:161], v[78:81], v[166:169], v[158:161]
	v_mfma_f32_16x16x32_bf16 v[126:129], v[62:65], v[174:177], v[126:129]
	v_mfma_f32_16x16x32_bf16 v[122:125], v[78:81], v[174:177], v[122:125]
	v_mfma_f32_16x16x32_bf16 v[110:113], v[62:65], v[210:213], v[110:113]
	v_mfma_f32_16x16x32_bf16 v[106:109], v[78:81], v[210:213], v[106:109]
	v_mfma_f32_16x16x32_bf16 v[94:97], v[62:65], v[218:221], v[94:97]
	v_mfma_f32_16x16x32_bf16 v[90:93], v[78:81], v[218:221], v[90:93]
	s_setprio 0
	s_setprio 1
	v_mfma_f32_16x16x32_bf16 v[134:137], v[138:141], v[154:157], v[134:137]
	v_mfma_f32_16x16x32_bf16 v[130:133], v[146:149], v[154:157], v[130:133]
	v_mfma_f32_16x16x32_bf16 v[118:121], v[138:141], v[170:173], v[118:121]
	v_mfma_f32_16x16x32_bf16 v[114:117], v[146:149], v[170:173], v[114:117]
	v_mfma_f32_16x16x32_bf16 v[102:105], v[138:141], v[206:209], v[102:105]
	v_mfma_f32_16x16x32_bf16 v[98:101], v[146:149], v[206:209], v[98:101]
	v_mfma_f32_16x16x32_bf16 v[86:89], v[138:141], v[214:217], v[86:89]
	v_mfma_f32_16x16x32_bf16 v[82:85], v[146:149], v[214:217], v[82:85]
	v_mfma_f32_16x16x32_bf16 v[134:137], v[142:145], v[166:169], v[134:137]
	v_mfma_f32_16x16x32_bf16 v[130:133], v[150:153], v[166:169], v[130:133]
	v_mfma_f32_16x16x32_bf16 v[118:121], v[142:145], v[174:177], v[118:121]
	v_mfma_f32_16x16x32_bf16 v[114:117], v[150:153], v[174:177], v[114:117]
	v_mfma_f32_16x16x32_bf16 v[102:105], v[142:145], v[210:213], v[102:105]
	v_mfma_f32_16x16x32_bf16 v[98:101], v[150:153], v[210:213], v[98:101]
	v_mfma_f32_16x16x32_bf16 v[86:89], v[142:145], v[218:221], v[86:89]
	v_mfma_f32_16x16x32_bf16 v[82:85], v[150:153], v[218:221], v[82:85]
	s_setprio 0
	s_barrier
	s_add_i32 s10, s21, s48
	v_lshl_add_u64 v[178:179], s[58:59], 0, v[198:199]
	s_mov_b32 m0, s10
	ds_read_b128 v[154:157], v239 offset:16384
	ds_read_b128 v[166:169], v239 offset:17408
	ds_read_b128 v[170:173], v239 offset:18432
	ds_read_b128 v[174:177], v239 offset:19456
	ds_read_b128 v[206:209], v239 offset:20480
	ds_read_b128 v[210:213], v239 offset:21504
	ds_read_b128 v[214:217], v239 offset:22528
	ds_read_b128 v[218:221], v239 offset:23552
	global_load_lds_dwordx4 v[178:179], off
	s_add_i32 m0, s10, 0x2000
	s_add_u32 s10, s58, 0x20000
	v_lshl_add_u64 v[180:181], s[58:59], 0, v[194:195]
	s_addc_u32 s11, s59, 0
	s_add_i32 s14, s14, s48
	global_load_lds_dwordx4 v[180:181], off
	v_lshl_add_u64 v[182:183], s[10:11], 0, v[198:199]
	s_mov_b32 m0, s14
	s_nop 0
	global_load_lds_dwordx4 v[182:183], off
	v_lshl_add_u64 v[182:183], s[10:11], 0, v[194:195]
	s_add_i32 m0, s14, 0x2000
	s_nop 0
	global_load_lds_dwordx4 v[182:183], off
	v_lshl_add_u64 v[182:183], s[60:61], 0, v[200:201]
	s_mov_b32 m0, s49
	s_nop 0
	global_load_lds_dwordx4 v[182:183], off
	v_lshl_add_u64 v[182:183], s[60:61], 0, v[196:197]
	s_mov_b32 m0, s76
	s_nop 0
	global_load_lds_dwordx4 v[182:183], off
	s_waitcnt vmcnt(8)
	s_waitcnt lgkmcnt(0)
	s_barrier
; #define PG8_STAGE(bufoff, gbase, voff) do { _Pragma("unroll") for (int _i = 0; _i < 2; ++_i) \
;         __builtin_amdgcn_global_load_lds((const unsigned*)((const char*)(gbase) + (voff)[_i]), (LAS unsigned*)(lds + (bufoff) + ldsw + _i * 8192), 16, 0, 0); } while (0)
; #define PG8_LDA(dst, b, h) do { _Pragma("unroll") for (int m = 0; m < 4; ++m) _Pragma("unroll") for (int k = 0; k < 2; ++k) dst[m][k] = *(const LAS bf16x8*)(lds + PG8_SA(b, h) + aoff + m * 2048 + k * 1024); } while (0)
; #define PG8_LDB(dst, b, h) do { _Pragma("unroll") for (int n = 0; n < 2; ++n) _Pragma("unroll") for (int k = 0; k < 2; ++k) dst[n][k] = *(const LAS bf16x8*)(lds + PG8_SB(b, h) + boff + n * 2048 + k * 1024); } while (0)
; #define PG8_MMA(ai, bj, At, Bt) do { __builtin_amdgcn_s_setprio(1); _Pragma("unroll") for (int m = 0; m < 4; ++m) _Pragma("unroll") for (int n = 0; n < 2; ++n) _Pragma("unroll") for (int k = 0; k < 2; ++k) \
;         acc[ai][bj][m][n] = __builtin_amdgcn_mfma_f32_16x16x32_bf16(Bt[n][k], At[m][k], acc[ai][bj][m][n], 0, 0, 0); __builtin_amdgcn_s_setprio(0); } while (0)
; #define PG8_WAIT_V(n) asm volatile("s_waitcnt vmcnt(" #n ")" ::: "memory")
; #define PG8_WAIT_L(n) asm volatile("s_waitcnt lgkmcnt(" #n ")" ::: "memory")
; #define PG8_BAR __builtin_amdgcn_s_barrier()
; #define PG8_SCHED __builtin_amdgcn_sched_barrier(0)
; template <class Epi, class Pre, bool AG = false>
; __device__ __forceinline__ void gemm_phase(LAS unsigned char* lds, const Gemm g, const StaticOrder& S, const Epi& E, const Pre& P) {
;     ...
;             PG8_WAIT_V(8); PG8_WAIT_L(0); PG8_BAR; PG8_MMA(1, 0, At, B0); PG8_MMA(1, 1, At, B1); PG8_BAR; PG8_SCHED;
;             PG8_LDB(B0, 1, 0); PG8_LDB(B1, 1, 1); PG8_SCHED; PG8_LDA(At, 1, 0); PG8_STAGE(PG8_SA(0, 1), a2 + hstepA, voffA);
;             PG8_WAIT_V(8); PG8_WAIT_L(0); PG8_BAR; PG8_MMA(0, 0, At, B0); PG8_MMA(0, 1, At, B1); PG8_BAR; PG8_SCHED;
	s_setprio 1
	s_waitcnt lgkmcnt(0)
	v_mfma_f32_16x16x32_bf16 v[70:73], v[58:61], v[154:157], v[70:73]
	v_mfma_f32_16x16x32_bf16 v[66:69], v[74:77], v[154:157], v[66:69]
	v_mfma_f32_16x16x32_bf16 v[46:49], v[58:61], v[170:173], v[46:49]
	v_mfma_f32_16x16x32_bf16 v[42:45], v[74:77], v[170:173], v[42:45]
	v_mfma_f32_16x16x32_bf16 v[30:33], v[58:61], v[206:209], v[30:33]
	v_mfma_f32_16x16x32_bf16 v[26:29], v[74:77], v[206:209], v[26:29]
	v_mfma_f32_16x16x32_bf16 v[14:17], v[58:61], v[214:217], v[14:17]
	v_mfma_f32_16x16x32_bf16 v[10:13], v[74:77], v[214:217], v[10:13]
	v_mfma_f32_16x16x32_bf16 v[70:73], v[62:65], v[166:169], v[70:73]
	v_mfma_f32_16x16x32_bf16 v[66:69], v[78:81], v[166:169], v[66:69]
	v_mfma_f32_16x16x32_bf16 v[46:49], v[62:65], v[174:177], v[46:49]
	v_mfma_f32_16x16x32_bf16 v[42:45], v[78:81], v[174:177], v[42:45]
	v_mfma_f32_16x16x32_bf16 v[30:33], v[62:65], v[210:213], v[30:33]
	v_mfma_f32_16x16x32_bf16 v[26:29], v[78:81], v[210:213], v[26:29]
	v_mfma_f32_16x16x32_bf16 v[14:17], v[62:65], v[218:221], v[14:17]
	v_mfma_f32_16x16x32_bf16 v[10:13], v[78:81], v[218:221], v[10:13]
	s_setprio 0
	s_setprio 1
	v_mfma_f32_16x16x32_bf16 v[54:57], v[138:141], v[154:157], v[54:57]
	v_mfma_f32_16x16x32_bf16 v[50:53], v[146:149], v[154:157], v[50:53]
	v_mfma_f32_16x16x32_bf16 v[38:41], v[138:141], v[170:173], v[38:41]
	v_mfma_f32_16x16x32_bf16 v[34:37], v[146:149], v[170:173], v[34:37]
	v_mfma_f32_16x16x32_bf16 v[22:25], v[138:141], v[206:209], v[22:25]
	v_mfma_f32_16x16x32_bf16 v[18:21], v[146:149], v[206:209], v[18:21]
	v_mfma_f32_16x16x32_bf16 v[6:9], v[138:141], v[214:217], v[6:9]
	v_mfma_f32_16x16x32_bf16 v[2:5], v[146:149], v[214:217], v[2:5]
	v_mfma_f32_16x16x32_bf16 v[54:57], v[142:145], v[166:169], v[54:57]
	v_mfma_f32_16x16x32_bf16 v[50:53], v[150:153], v[166:169], v[50:53]
	v_mfma_f32_16x16x32_bf16 v[38:41], v[142:145], v[174:177], v[38:41]
	v_mfma_f32_16x16x32_bf16 v[34:37], v[150:153], v[174:177], v[34:37]
	v_mfma_f32_16x16x32_bf16 v[22:25], v[142:145], v[210:213], v[22:25]
	v_mfma_f32_16x16x32_bf16 v[18:21], v[150:153], v[210:213], v[18:21]
	v_mfma_f32_16x16x32_bf16 v[6:9], v[142:145], v[218:221], v[6:9]
	v_mfma_f32_16x16x32_bf16 v[2:5], v[150:153], v[218:221], v[2:5]
	s_setprio 0
	s_barrier
	s_add_i32 s14, 0, 0x18000
	v_add_u32_e32 v0, s14, v238
	s_add_i32 s21, 0, 0x1c000
	ds_read_b128 v[58:61], v0
	ds_read_b128 v[62:65], v0 offset:1024
	ds_read_b128 v[74:77], v0 offset:2048
	ds_read_b128 v[78:81], v0 offset:3072
	v_add_u32_e32 v0, s21, v238
	ds_read_b128 v[138:141], v0
	ds_read_b128 v[142:145], v0 offset:1024
	ds_read_b128 v[146:149], v0 offset:2048
	ds_read_b128 v[150:153], v0 offset:3072
	s_add_u32 s10, s60, 0x1000
	s_addc_u32 s11, s61, 0
	s_mov_b32 m0, s77
	v_lshl_add_u64 v[182:183], s[10:11], 0, v[200:201]
	ds_read_b128 v[154:157], v239 offset:32768
	ds_read_b128 v[166:169], v239 offset:33792
	ds_read_b128 v[170:173], v239 offset:34816
	ds_read_b128 v[174:177], v239 offset:35840
	ds_read_b128 v[206:209], v239 offset:36864
	ds_read_b128 v[210:213], v239 offset:37888
	ds_read_b128 v[214:217], v239 offset:38912
	ds_read_b128 v[218:221], v239 offset:39936
	global_load_lds_dwordx4 v[182:183], off
	v_lshl_add_u64 v[182:183], s[10:11], 0, v[196:197]
	s_mov_b32 m0, s84
	s_nop 0
	global_load_lds_dwordx4 v[182:183], off
	s_waitcnt vmcnt(8)
	s_waitcnt lgkmcnt(0)
	s_barrier
	s_setprio 1
	s_waitcnt lgkmcnt(0)
	v_mfma_f32_16x16x32_bf16 v[162:165], v[58:61], v[154:157], v[162:165]
	v_mfma_f32_16x16x32_bf16 v[158:161], v[74:77], v[154:157], v[158:161]
	v_mfma_f32_16x16x32_bf16 v[126:129], v[58:61], v[170:173], v[126:129]
	v_mfma_f32_16x16x32_bf16 v[122:125], v[74:77], v[170:173], v[122:125]
	v_mfma_f32_16x16x32_bf16 v[110:113], v[58:61], v[206:209], v[110:113]
	v_mfma_f32_16x16x32_bf16 v[106:109], v[74:77], v[206:209], v[106:109]
	v_mfma_f32_16x16x32_bf16 v[94:97], v[58:61], v[214:217], v[94:97]
	v_mfma_f32_16x16x32_bf16 v[90:93], v[74:77], v[214:217], v[90:93]
	v_mfma_f32_16x16x32_bf16 v[162:165], v[62:65], v[166:169], v[162:165]
	v_mfma_f32_16x16x32_bf16 v[158:161], v[78:81], v[166:169], v[158:161]
	v_mfma_f32_16x16x32_bf16 v[126:129], v[62:65], v[174:177], v[126:129]
	v_mfma_f32_16x16x32_bf16 v[122:125], v[78:81], v[174:177], v[122:125]
	v_mfma_f32_16x16x32_bf16 v[110:113], v[62:65], v[210:213], v[110:113]
	v_mfma_f32_16x16x32_bf16 v[106:109], v[78:81], v[210:213], v[106:109]
	v_mfma_f32_16x16x32_bf16 v[94:97], v[62:65], v[218:221], v[94:97]
	v_mfma_f32_16x16x32_bf16 v[90:93], v[78:81], v[218:221], v[90:93]
	s_setprio 0
	s_setprio 1
	v_mfma_f32_16x16x32_bf16 v[134:137], v[138:141], v[154:157], v[134:137]
	v_mfma_f32_16x16x32_bf16 v[130:133], v[146:149], v[154:157], v[130:133]
	v_mfma_f32_16x16x32_bf16 v[118:121], v[138:141], v[170:173], v[118:121]
	v_mfma_f32_16x16x32_bf16 v[114:117], v[146:149], v[170:173], v[114:117]
	v_mfma_f32_16x16x32_bf16 v[102:105], v[138:141], v[206:209], v[102:105]
	v_mfma_f32_16x16x32_bf16 v[98:101], v[146:149], v[206:209], v[98:101]
	v_mfma_f32_16x16x32_bf16 v[86:89], v[138:141], v[214:217], v[86:89]
	v_mfma_f32_16x16x32_bf16 v[82:85], v[146:149], v[214:217], v[82:85]
	v_mfma_f32_16x16x32_bf16 v[134:137], v[142:145], v[166:169], v[134:137]
	v_mfma_f32_16x16x32_bf16 v[130:133], v[150:153], v[166:169], v[130:133]
	v_mfma_f32_16x16x32_bf16 v[118:121], v[142:145], v[174:177], v[118:121]
	v_mfma_f32_16x16x32_bf16 v[114:117], v[150:153], v[174:177], v[114:117]
	v_mfma_f32_16x16x32_bf16 v[102:105], v[142:145], v[210:213], v[102:105]
	v_mfma_f32_16x16x32_bf16 v[98:101], v[150:153], v[210:213], v[98:101]
	v_mfma_f32_16x16x32_bf16 v[86:89], v[142:145], v[218:221], v[86:89]
	v_mfma_f32_16x16x32_bf16 v[82:85], v[150:153], v[218:221], v[82:85]
	s_setprio 0
	s_barrier
; #define PG8_STAGE(bufoff, gbase, voff) do { _Pragma("unroll") for (int _i = 0; _i < 2; ++_i) \
;         __builtin_amdgcn_global_load_lds((const unsigned*)((const char*)(gbase) + (voff)[_i]), (LAS unsigned*)(lds + (bufoff) + ldsw + _i * 8192), 16, 0, 0); } while (0)
; #define PG8_LDA(dst, b, h) do { _Pragma("unroll") for (int m = 0; m < 4; ++m) _Pragma("unroll") for (int k = 0; k < 2; ++k) dst[m][k] = *(const LAS bf16x8*)(lds + PG8_SA(b, h) + aoff + m * 2048 + k * 1024); } while (0)
; #define PG8_MMA(ai, bj, At, Bt) do { __builtin_amdgcn_s_setprio(1); _Pragma("unroll") for (int m = 0; m < 4; ++m) _Pragma("unroll") for (int n = 0; n < 2; ++n) _Pragma("unroll") for (int k = 0; k < 2; ++k) \
;         acc[ai][bj][m][n] = __builtin_amdgcn_mfma_f32_16x16x32_bf16(Bt[n][k], At[m][k], acc[ai][bj][m][n], 0, 0, 0); __builtin_amdgcn_s_setprio(0); } while (0)
; #define PG8_WAIT_V(n) asm volatile("s_waitcnt vmcnt(" #n ")" ::: "memory")
; template <class Epi, class Pre, bool AG = false>
; __device__ __forceinline__ void gemm_phase(LAS unsigned char* lds, const Gemm g, const StaticOrder& S, const Epi& E, const Pre& P) {
;     ...
;             PG8_LDA(At, 1, 1); PG8_STAGE(PG8_SB(1, 0), b3, voffB); PG8_STAGE(PG8_SB(1, 1), b3 + hstep, voffB); PG8_STAGE(PG8_SA(1, 0), a3, voffA);
;             PG8_WAIT_V(8); PG8_WAIT_L(0); PG8_BAR; PG8_MMA(1, 0, At, B0); PG8_MMA(1, 1, At, B1); PG8_BAR; PG8_SCHED;
;         }
;         if (wr == 0) PG8_BAR;
;         {
;             int te = threadIdx.x; asm volatile("" : "+v"(te));
;             const int le = te & 63;
;             E(acc, cur, ui, wr, wc, le & 15, le >> 4);
;     __device__ __forceinline__ void operator()(const AccT& acc, const pg8::Unit& u, int ui, int wr, int wc, int fr, int fq) const {
;         const int row0 = u.pm * 256 + wr * 64 + fr, col0 = u.pn * 256 + wc * 32 + 8 * fq;
;         f32x4 bv[2][2];
; #pragma unroll
;         for (int bj = 0; bj < 2; ++bj)
; #pragma unroll
;             for (int n = 0; n < 2; ++n) bv[bj][n] = *(const f32x4*)(bias + col0 + 128 * bj + 4 * n);
; #pragma unroll
;         for (int ai = 0; ai < 2; ++ai) {
;             u32x4 zv[4][2];
; #pragma unroll
;             for (int m = 0; m < 4; ++m)
; #pragma unroll
;                 for (int bj = 0; bj < 2; ++bj) { const int col = col0 + 128 * bj; zv[m][bj] = *(const u32x4*)(zg + ((size_t)(col >> 4) * M + (row0 + ai * 128 + m * 16)) * 16 + (col & 15)); }
	s_add_i32 s10, s14, s48
	v_lshl_add_u64 v[178:179], v[178:179], 0, s[66:67]
	s_mov_b32 m0, s10
	ds_read_b128 v[154:157], v239 offset:49152
	ds_read_b128 v[166:169], v239 offset:50176
	ds_read_b128 v[170:173], v239 offset:51200
	ds_read_b128 v[174:177], v239 offset:52224
	ds_read_b128 v[206:209], v239 offset:53248
	ds_read_b128 v[210:213], v239 offset:54272
	ds_read_b128 v[214:217], v239 offset:55296
	ds_read_b128 v[218:221], v239 offset:56320
	global_load_lds_dwordx4 v[178:179], off
	s_add_i32 m0, s10, 0x2000
	s_add_u32 s10, s58, 0x20080
	v_lshl_add_u64 v[178:179], v[180:181], 0, s[66:67]
	s_addc_u32 s11, s59, 0
	s_add_i32 s14, s21, s48
	global_load_lds_dwordx4 v[178:179], off
	v_lshl_add_u64 v[178:179], s[10:11], 0, v[198:199]
	s_mov_b32 m0, s14
	s_nop 0
	global_load_lds_dwordx4 v[178:179], off
	v_lshl_add_u64 v[178:179], s[10:11], 0, v[194:195]
	s_add_i32 m0, s14, 0x2000
	s_nop 0
	global_load_lds_dwordx4 v[178:179], off
	v_lshl_add_u64 v[178:179], s[56:57], 0, v[200:201]
	s_mov_b32 m0, s24
	s_nop 0
	global_load_lds_dwordx4 v[178:179], off
	v_lshl_add_u64 v[178:179], s[56:57], 0, v[196:197]
	s_mov_b32 m0, s25
	s_nop 0
	global_load_lds_dwordx4 v[178:179], off
	s_waitcnt vmcnt(8)
	s_waitcnt lgkmcnt(0)
	s_barrier
	s_setprio 1
	s_waitcnt lgkmcnt(0)
	v_mfma_f32_16x16x32_bf16 v[70:73], v[58:61], v[154:157], v[70:73]
	v_mfma_f32_16x16x32_bf16 v[66:69], v[74:77], v[154:157], v[66:69]
	v_mfma_f32_16x16x32_bf16 v[46:49], v[58:61], v[170:173], v[46:49]
	v_mfma_f32_16x16x32_bf16 v[42:45], v[74:77], v[170:173], v[42:45]
	v_mfma_f32_16x16x32_bf16 v[30:33], v[58:61], v[206:209], v[30:33]
	v_mfma_f32_16x16x32_bf16 v[26:29], v[74:77], v[206:209], v[26:29]
	v_mfma_f32_16x16x32_bf16 v[14:17], v[58:61], v[214:217], v[14:17]
	v_mfma_f32_16x16x32_bf16 v[10:13], v[74:77], v[214:217], v[10:13]
	v_mfma_f32_16x16x32_bf16 v[70:73], v[62:65], v[166:169], v[70:73]
	v_mfma_f32_16x16x32_bf16 v[66:69], v[78:81], v[166:169], v[66:69]
	v_mfma_f32_16x16x32_bf16 v[46:49], v[62:65], v[174:177], v[46:49]
	v_mfma_f32_16x16x32_bf16 v[42:45], v[78:81], v[174:177], v[42:45]
	v_mfma_f32_16x16x32_bf16 v[30:33], v[62:65], v[210:213], v[30:33]
	v_mfma_f32_16x16x32_bf16 v[26:29], v[78:81], v[210:213], v[26:29]
	v_mfma_f32_16x16x32_bf16 v[14:17], v[62:65], v[218:221], v[14:17]
	v_mfma_f32_16x16x32_bf16 v[10:13], v[78:81], v[218:221], v[10:13]
	s_setprio 0
	s_setprio 1
	v_mfma_f32_16x16x32_bf16 v[54:57], v[138:141], v[154:157], v[54:57]
	v_mfma_f32_16x16x32_bf16 v[50:53], v[146:149], v[154:157], v[50:53]
	v_mfma_f32_16x16x32_bf16 v[38:41], v[138:141], v[170:173], v[38:41]
	v_mfma_f32_16x16x32_bf16 v[34:37], v[146:149], v[170:173], v[34:37]
	v_mfma_f32_16x16x32_bf16 v[22:25], v[138:141], v[206:209], v[22:25]
	v_mfma_f32_16x16x32_bf16 v[18:21], v[146:149], v[206:209], v[18:21]
	v_mfma_f32_16x16x32_bf16 v[6:9], v[138:141], v[214:217], v[6:9]
	v_mfma_f32_16x16x32_bf16 v[2:5], v[146:149], v[214:217], v[2:5]
	v_mfma_f32_16x16x32_bf16 v[54:57], v[142:145], v[166:169], v[54:57]
	v_mfma_f32_16x16x32_bf16 v[50:53], v[150:153], v[166:169], v[50:53]
	v_mfma_f32_16x16x32_bf16 v[38:41], v[142:145], v[174:177], v[38:41]
	v_mfma_f32_16x16x32_bf16 v[34:37], v[150:153], v[174:177], v[34:37]
	v_mfma_f32_16x16x32_bf16 v[22:25], v[142:145], v[210:213], v[22:25]
	v_mfma_f32_16x16x32_bf16 v[18:21], v[150:153], v[210:213], v[18:21]
	v_mfma_f32_16x16x32_bf16 v[6:9], v[142:145], v[218:221], v[6:9]
	v_mfma_f32_16x16x32_bf16 v[2:5], v[150:153], v[218:221], v[2:5]
	s_setprio 0
	s_barrier
	s_add_i32 s87, s87, 2
	s_add_u32 vcc_lo, vcc_lo, 0x100
	s_addc_u32 vcc_hi, vcc_hi, 0
	s_cmp_gt_u32 s87, 5
	s_mov_b64 s[10:11], s[54:55]
	s_cbranch_scc0 .LBB0_741
	s_and_b64 vcc, exec, s[94:95]
	s_cbranch_vccz .LBB0_744
	s_barrier
.LBB0_744:
	s_mov_b32 s101, s62
	s_mov_b32 s99, 0
.Lfold_glu_again:
	v_mov_b32_e32 v0, v234
	s_lshl_b32 s11, s62, 8
	s_or_b32 s11, s11, s20
	v_bfe_u32 v138, v0, 4, 2
	v_lshl_or_b32 v206, v138, 3, s11
	v_ashrrev_i32_e32 v207, 31, v206
	v_lshl_add_u64 v[62:63], v[206:207], 2, s[46:47]
	global_load_dwordx4 v[74:77], v[62:63], off offset:16
	global_load_dwordx4 v[78:81], v[62:63], off
	global_load_dwordx4 v[58:61], v[62:63], off offset:528
	s_nop 0
	global_load_dwordx4 v[62:65], v[62:63], off offset:512
	s_lshl_b32 s10, s86, 8
	s_add_i32 s10, s10, s38
	v_and_or_b32 v214, v0, 15, s10
	v_cmp_eq_u32_e32 vcc, 0, v138
	v_and_b32_e32 v0, 16, v0
	v_ashrrev_i32_e32 v138, 4, v206
	v_ashrrev_i32_e32 v215, 31, v214
	v_lshl_add_u64 v[208:209], s[0:1], 0, v[0:1]
	v_ashrrev_i32_e32 v139, 31, v138
	v_lshlrev_b64 v[228:229], 5, v[214:215]
	v_lshlrev_b64 v[210:211], 19, v[138:139]
	v_lshl_add_u64 v[140:141], v[208:209], 0, v[228:229]
	v_lshl_add_u64 v[142:143], v[140:141], 0, v[210:211]
	global_load_dwordx4 v[174:177], v[142:143], off
	v_or_b32_e32 v138, 8, v138
	v_ashrrev_i32_e32 v139, 31, v138
	v_lshlrev_b64 v[212:213], 19, v[138:139]
	v_lshl_add_u64 v[138:139], v[140:141], 0, v[212:213]
	global_load_dwordx4 v[170:173], v[138:139], off
	v_or_b32_e32 v226, 16, v214
	v_ashrrev_i32_e32 v227, 31, v226
	v_lshlrev_b64 v[224:225], 5, v[226:227]
	v_or_b32_e32 v222, 32, v214
	v_lshl_add_u64 v[138:139], v[208:209], 0, v[224:225]
	v_ashrrev_i32_e32 v223, 31, v222
	v_lshl_add_u64 v[140:141], v[138:139], 0, v[210:211]
	v_lshl_add_u64 v[138:139], v[138:139], 0, v[212:213]
	v_lshlrev_b64 v[220:221], 5, v[222:223]
	v_or_b32_e32 v218, 48, v214
	global_load_dwordx4 v[166:169], v[140:141], off
	global_load_dwordx4 v[154:157], v[138:139], off
	v_lshl_add_u64 v[138:139], v[208:209], 0, v[220:221]
	v_ashrrev_i32_e32 v219, 31, v218
	v_lshl_add_u64 v[140:141], v[138:139], 0, v[210:211]
	v_lshl_add_u64 v[138:139], v[138:139], 0, v[212:213]
	v_lshlrev_b64 v[216:217], 5, v[218:219]
	global_load_dwordx4 v[150:153], v[140:141], off
	global_load_dwordx4 v[146:149], v[138:139], off
	v_lshl_add_u64 v[138:139], v[208:209], 0, v[216:217]
	v_lshl_add_u64 v[140:141], v[138:139], 0, v[210:211]
	v_lshl_add_u64 v[138:139], v[138:139], 0, v[212:213]
	global_load_dwordx4 v[142:145], v[140:141], off
	s_lshl_b32 s54, s62, 2
	global_load_dwordx4 v[138:141], v[138:139], off
	s_ashr_i32 s55, s54, 31
	s_waitcnt vmcnt(0)
; __device__ __forceinline__ unsigned pk2(float lo, float hi) { unsigned r; asm("v_cvt_pk_bf16_f32 %0, %1, %2" : "=v"(r) : "v"(lo), "v"(hi)); return r; }
; __device__ __forceinline__ float bflo(unsigned w) { return __uint_as_float(w << 16); }
; __device__ __forceinline__ float bfhi(unsigned w) { return __uint_as_float(w & 0xffff0000u); }
; __device__ __forceinline__ float sigmoidf_(float x) { return __builtin_amdgcn_rcpf(1.0f + __expf(-x)); }
;     __device__ __forceinline__ void operator()(const AccT& acc, const pg8::Unit& u, int ui, int wr, int wc, int fr, int fq) const {
;     ...
;             for (int m = 0; m < 4; ++m) {
;                 const int r = row0 + ai * 128 + m * 16; float ss = 0.f;
; #pragma unroll
;                 for (int bj = 0; bj < 2; ++bj) {
;                     const u32x4 zw = zv[m][bj];
;                     const f32x4 p0 = acc[ai][bj][m][0] + bv[bj][0], p1 = acc[ai][bj][m][1] + bv[bj][1];
;                     const float o0 = bflo(zw.x) * sigmoidf_(p0.x), o1 = bfhi(zw.x) * sigmoidf_(p0.y), o2 = bflo(zw.y) * sigmoidf_(p0.z), o3 = bfhi(zw.y) * sigmoidf_(p0.w);
;                     const float o4 = bflo(zw.z) * sigmoidf_(p1.x), o5 = bfhi(zw.z) * sigmoidf_(p1.y), o6 = bflo(zw.w) * sigmoidf_(p1.z), o7 = bfhi(zw.w) * sigmoidf_(p1.w);
;                     ss += (o0 * o0 + o1 * o1) + (o2 * o2 + o3 * o3) + (o4 * o4 + o5 * o5) + (o6 * o6 + o7 * o7);
;                     u32x4 w; w.x = pk2(o0, o1); w.y = pk2(o2, o3); w.z = pk2(o4, o5); w.w = pk2(o6, o7);
;                     *(u32x4*)(ys + (size_t)r * ldy + col0 + 128 * bj) = w;
;                 }
;                 ss += __shfl_xor(ss, 16); ss += __shfl_xor(ss, 32); if (fq == 0) part_s[(size_t)r * 8 + u.pn * 4 + wc] = ss;
	v_pk_add_f32 v[158:159], v[158:159], v[74:75]
	v_pk_add_f32 v[162:163], v[162:163], v[78:79]
	v_pk_add_f32 v[164:165], v[164:165], v[80:81]
	v_mul_f32_e32 v162, 0xbfb8aa3b, v162
	v_exp_f32_e32 v162, v162
	v_mul_f32_e32 v163, 0xbfb8aa3b, v163
	v_exp_f32_e32 v163, v163
	v_mul_f32_e32 v164, 0xbfb8aa3b, v164
	v_exp_f32_e32 v164, v164
	v_mul_f32_e32 v165, 0xbfb8aa3b, v165
	v_exp_f32_e32 v165, v165
	v_mul_f32_e32 v158, 0xbfb8aa3b, v158
	v_pk_add_f32 v[160:161], v[160:161], v[76:77]
	v_add_f32_e32 v162, 1.0, v162
	v_exp_f32_e32 v158, v158
	v_mul_f32_e32 v159, 0xbfb8aa3b, v159
	v_rcp_f32_e32 v162, v162
	v_add_f32_e32 v163, 1.0, v163
	v_exp_f32_e32 v159, v159
	v_mul_f32_e32 v160, 0xbfb8aa3b, v160
	v_rcp_f32_e32 v163, v163
	v_add_f32_e32 v164, 1.0, v164
	v_exp_f32_e32 v160, v160
	v_mul_f32_e32 v161, 0xbfb8aa3b, v161
	v_rcp_f32_e32 v164, v164
	v_add_f32_e32 v165, 1.0, v165
	v_exp_f32_e32 v161, v161
	v_lshlrev_b32_e32 v0, 16, v174
	v_rcp_f32_e32 v165, v165
	v_add_f32_e32 v158, 1.0, v158
	v_mul_f32_e32 v0, v162, v0
	v_and_b32_e32 v162, 0xffff0000, v174
	v_rcp_f32_e32 v158, v158
	v_add_f32_e32 v159, 1.0, v159
	v_mul_f32_e32 v162, v163, v162
	v_lshlrev_b32_e32 v163, 16, v175
	v_rcp_f32_e32 v159, v159
	v_add_f32_e32 v160, 1.0, v160
	v_mul_f32_e32 v163, v164, v163
	v_and_b32_e32 v164, 0xffff0000, v175
	v_rcp_f32_e32 v160, v160
	v_add_f32_e32 v161, 1.0, v161
	v_mul_f32_e32 v164, v165, v164
	v_lshlrev_b32_e32 v165, 16, v176
	v_rcp_f32_e32 v161, v161
	v_pk_add_f32 v[134:135], v[134:135], v[62:63]
	v_mul_f32_e32 v158, v158, v165
	v_and_b32_e32 v165, 0xffff0000, v176
	v_mul_f32_e32 v134, 0xbfb8aa3b, v134
	v_mul_f32_e32 v159, v159, v165
	v_lshlrev_b32_e32 v165, 16, v177
	v_pk_add_f32 v[136:137], v[136:137], v[64:65]
	v_exp_f32_e32 v134, v134
	v_mul_f32_e32 v135, 0xbfb8aa3b, v135
	v_mul_f32_e32 v165, v160, v165
	v_and_b32_e32 v160, 0xffff0000, v177
	v_exp_f32_e32 v135, v135
	v_mul_f32_e32 v136, 0xbfb8aa3b, v136
	v_mul_f32_e32 v174, v161, v160
	v_mul_f32_e32 v160, v162, v162
	v_mul_f32_e32 v161, v164, v164
	v_pk_add_f32 v[130:131], v[130:131], v[58:59]
	v_exp_f32_e32 v136, v136
	v_mul_f32_e32 v137, 0xbfb8aa3b, v137
	v_fmac_f32_e32 v160, v0, v0
	v_fmac_f32_e32 v161, v163, v163
	v_exp_f32_e32 v137, v137
	v_mul_f32_e32 v130, 0xbfb8aa3b, v130
	v_add_f32_e32 v160, v160, v161
	v_mul_f32_e32 v161, v159, v159
	v_add_f32_e32 v134, 1.0, v134
	v_exp_f32_e32 v130, v130
	v_mul_f32_e32 v131, 0xbfb8aa3b, v131
	v_fmac_f32_e32 v161, v158, v158
	v_rcp_f32_e32 v134, v134
	v_add_f32_e32 v135, 1.0, v135
	v_exp_f32_e32 v131, v131
	v_add_f32_e32 v160, v161, v160
	v_mul_f32_e32 v161, v174, v174
	v_rcp_f32_e32 v135, v135
	v_add_f32_e32 v136, 1.0, v136
	v_fmac_f32_e32 v161, v165, v165
	v_rcp_f32_e32 v136, v136
	v_add_f32_e32 v137, 1.0, v137
	v_add_f32_e32 v175, v161, v160
	v_cvt_pk_bf16_f32 v160, v0, v162
	v_lshlrev_b32_e32 v0, 16, v170
	v_rcp_f32_e32 v137, v137
	v_add_f32_e32 v130, 1.0, v130
	v_mul_f32_e32 v0, v134, v0
	v_and_b32_e32 v134, 0xffff0000, v170
	v_rcp_f32_e32 v130, v130
	v_add_f32_e32 v131, 1.0, v131
	v_mul_f32_e32 v134, v135, v134
	v_lshlrev_b32_e32 v135, 16, v171
	v_rcp_f32_e32 v131, v131
	v_cvt_pk_bf16_f32 v162, v158, v159
	v_lshlrev_b64 v[158:159], 11, v[214:215]
	v_mul_f32_e32 v135, v136, v135
	v_and_b32_e32 v136, 0xffff0000, v171
	v_lshl_add_u64 v[158:159], s[70:71], 0, v[158:159]
	v_mul_f32_e32 v136, v137, v136
	v_lshlrev_b32_e32 v137, 16, v172
	v_lshl_add_u64 v[158:159], v[206:207], 1, v[158:159]
	v_pk_add_f32 v[132:133], v[132:133], v[60:61]
	v_mul_f32_e32 v137, v130, v137
	v_and_b32_e32 v130, 0xffff0000, v172
	v_cvt_pk_bf16_f32 v161, v163, v164
	v_cvt_pk_bf16_f32 v163, v165, v174
	global_store_dwordx4 v[158:159], v[160:163], off
	s_nop 1
	v_mul_f32_e32 v160, v131, v130
	v_mul_f32_e32 v131, 0xbfb8aa3b, v132
	v_exp_f32_e32 v131, v131
	v_lshlrev_b32_e32 v130, 16, v173
	v_cvt_pk_bf16_f32 v132, v137, v160
	v_add_f32_e32 v131, 1.0, v131
	v_rcp_f32_e32 v131, v131
	s_nop 0
	v_mul_f32_e32 v161, v131, v130
	v_mul_f32_e32 v131, 0xbfb8aa3b, v133
	v_exp_f32_e32 v131, v131
	v_and_b32_e32 v130, 0xffff0000, v173
	v_add_f32_e32 v131, 1.0, v131
	v_rcp_f32_e32 v131, v131
	s_nop 0
	v_mul_f32_e32 v133, v131, v130
	v_mul_f32_e32 v130, v134, v134
	v_mul_f32_e32 v131, v136, v136
	v_fmac_f32_e32 v130, v0, v0
	v_fmac_f32_e32 v131, v135, v135
	v_add_f32_e32 v130, v130, v131
	v_mul_f32_e32 v131, v160, v160
	v_fmac_f32_e32 v131, v137, v137
	v_add_f32_e32 v130, v130, v131
	v_mul_f32_e32 v131, v133, v133
	v_fmac_f32_e32 v131, v161, v161
	v_add_f32_e32 v130, v131, v130
	v_add_f32_e32 v162, v175, v130
	v_cvt_pk_bf16_f32 v130, v0, v134
	v_cvt_pk_bf16_f32 v131, v135, v136
	v_cvt_pk_bf16_f32 v133, v161, v133
	global_store_dwordx4 v[158:159], v[130:133], off offset:256
	v_xor_b32_e32 v0, 16, v231
	s_nop 0
	v_and_b32_e32 v130, 64, v231
	v_add_u32_e32 v130, 64, v130
	v_cmp_lt_i32_e64 s[10:11], v0, v130
	v_xor_b32_e32 v132, 32, v231
	s_nop 0
	v_cndmask_b32_e64 v0, v231, v0, s[10:11]
	v_lshlrev_b32_e32 v0, 2, v0
	ds_bpermute_b32 v131, v0, v162
	v_cmp_lt_i32_e64 s[10:11], v132, v130
	s_waitcnt lgkmcnt(0)
	v_add_f32_e32 v131, v162, v131
	v_cndmask_b32_e64 v130, v231, v132, s[10:11]
	v_lshlrev_b32_e32 v130, 2, v130
	ds_bpermute_b32 v132, v130, v131
	s_and_saveexec_b64 s[10:11], vcc
	s_cbranch_execz .LBB0_746
	v_lshl_add_u64 v[134:135], s[78:79], 0, v[228:229]
	v_lshl_add_u64 v[134:135], s[54:55], 2, v[134:135]
	s_lshl_b32 s62, s85, 2
	v_lshl_add_u64 v[134:135], v[134:135], 0, s[62:63]
	s_waitcnt lgkmcnt(0)
	v_add_f32_e32 v131, v131, v132
	global_store_dword v[134:135], v131, off

; __device__ __forceinline__ unsigned pk2(float lo, float hi) { unsigned r; asm("v_cvt_pk_bf16_f32 %0, %1, %2" : "=v"(r) : "v"(lo), "v"(hi)); return r; }
; __device__ __forceinline__ float bflo(unsigned w) { return __uint_as_float(w << 16); }
; __device__ __forceinline__ float bfhi(unsigned w) { return __uint_as_float(w & 0xffff0000u); }
; __device__ __forceinline__ float sigmoidf_(float x) { return __builtin_amdgcn_rcpf(1.0f + __expf(-x)); }
;     __device__ __forceinline__ void operator()(const AccT& acc, const pg8::Unit& u, int ui, int wr, int wc, int fr, int fq) const {
;     ...
;         for (int ai = 0; ai < 2; ++ai) {
;             u32x4 zv[4][2];
; #pragma unroll
;             for (int m = 0; m < 4; ++m)
; #pragma unroll
;                 for (int bj = 0; bj < 2; ++bj) { const int col = col0 + 128 * bj; zv[m][bj] = *(const u32x4*)(zg + ((size_t)(col >> 4) * M + (row0 + ai * 128 + m * 16)) * 16 + (col & 15)); }
; #pragma unroll
;             for (int m = 0; m < 4; ++m) {
;                 const int r = row0 + ai * 128 + m * 16; float ss = 0.f;
; #pragma unroll
;                 for (int bj = 0; bj < 2; ++bj) {
;                     const u32x4 zw = zv[m][bj];
;                     const f32x4 p0 = acc[ai][bj][m][0] + bv[bj][0], p1 = acc[ai][bj][m][1] + bv[bj][1];
;                     const float o0 = bflo(zw.x) * sigmoidf_(p0.x), o1 = bfhi(zw.x) * sigmoidf_(p0.y), o2 = bflo(zw.y) * sigmoidf_(p0.z), o3 = bfhi(zw.y) * sigmoidf_(p0.w);
;                     const float o4 = bflo(zw.z) * sigmoidf_(p1.x), o5 = bfhi(zw.z) * sigmoidf_(p1.y), o6 = bflo(zw.w) * sigmoidf_(p1.z), o7 = bfhi(zw.w) * sigmoidf_(p1.w);
;                     ss += (o0 * o0 + o1 * o1) + (o2 * o2 + o3 * o3) + (o4 * o4 + o5 * o5) + (o6 * o6 + o7 * o7);
;                     u32x4 w; w.x = pk2(o0, o1); w.y = pk2(o2, o3); w.z = pk2(o4, o5); w.w = pk2(o6, o7);
;                     *(u32x4*)(ys + (size_t)r * ldy + col0 + 128 * bj) = w;
;                 }
;                 ss += __shfl_xor(ss, 16); ss += __shfl_xor(ss, 32); if (fq == 0) part_s[(size_t)r * 8 + u.pn * 4 + wc] = ss;
;             }
;         }
.LBB0_752:
	s_or_b64 exec, exec, s[10:11]
	s_cmp_lg_u32 s99, 0
	s_cbranch_scc1 .Lfold_glu_done
	s_mov_b32 s99, 1
	s_mov_b32 s62, s101
	s_add_i32 s38, s38, 0x80
	s_nop 1
	v_mov_b64_e32 v[162:163], v[70:71]
	v_mov_b64_e32 v[164:165], v[72:73]
	v_mov_b64_e32 v[158:159], v[66:67]
	v_mov_b64_e32 v[160:161], v[68:69]
	v_mov_b64_e32 v[126:127], v[46:47]
	v_mov_b64_e32 v[128:129], v[48:49]
	v_mov_b64_e32 v[122:123], v[42:43]
	v_mov_b64_e32 v[124:125], v[44:45]
	v_mov_b64_e32 v[110:111], v[30:31]
	v_mov_b64_e32 v[112:113], v[32:33]
	v_mov_b64_e32 v[106:107], v[26:27]
	v_mov_b64_e32 v[108:109], v[28:29]
	v_mov_b64_e32 v[94:95], v[14:15]
	v_mov_b64_e32 v[96:97], v[16:17]
	v_mov_b64_e32 v[90:91], v[10:11]
	v_mov_b64_e32 v[92:93], v[12:13]
	v_mov_b64_e32 v[134:135], v[54:55]
	v_mov_b64_e32 v[136:137], v[56:57]
	v_mov_b64_e32 v[130:131], v[50:51]
	v_mov_b64_e32 v[132:133], v[52:53]
	v_mov_b64_e32 v[118:119], v[38:39]
	v_mov_b64_e32 v[120:121], v[40:41]
	v_mov_b64_e32 v[114:115], v[34:35]
	v_mov_b64_e32 v[116:117], v[36:37]
	v_mov_b64_e32 v[102:103], v[22:23]
	v_mov_b64_e32 v[104:105], v[24:25]
	v_mov_b64_e32 v[98:99], v[18:19]
	v_mov_b64_e32 v[100:101], v[20:21]
	v_mov_b64_e32 v[86:87], v[6:7]
	v_mov_b64_e32 v[88:89], v[8:9]
	v_mov_b64_e32 v[82:83], v[2:3]
	v_mov_b64_e32 v[84:85], v[4:5]
	s_branch .Lfold_glu_again
.Lfold_glu_done:
	s_sub_i32 s38, s38, 0x80

; __device__ __forceinline__ unsigned pk2(float lo, float hi) { unsigned r; asm("v_cvt_pk_bf16_f32 %0, %1, %2" : "=v"(r) : "v"(lo), "v"(hi)); return r; }
; __device__ __forceinline__ float bflo(unsigned w) { return __uint_as_float(w << 16); }
; __device__ __forceinline__ float bfhi(unsigned w) { return __uint_as_float(w & 0xffff0000u); }
; #define PG8_BAR __builtin_amdgcn_s_barrier()
; template <class Epi, class Pre, bool AG = false>
; __device__ __forceinline__ void gemm_phase(LAS unsigned char* lds, const Gemm g, const StaticOrder& S, const Epi& E, const Pre& P) {
;     ...
;         if (wr == 0) PG8_BAR;
;     __device__ __forceinline__ void operator()(const AccT& acc, const pg8::Unit& u, int ui, int wr, int wc, int fr, int fq) const {
;         const int row0 = u.pm * 256 + wr * 64 + fr, col0 = u.pn * 256 + wc * 32 + 8 * fq;
; #pragma unroll
;         for (int ai = 0; ai < 2; ++ai) {
;             u32x4 hv[4][2];
; #pragma unroll
;             for (int m = 0; m < 4; ++m)
; #pragma unroll
;                 for (int bj = 0; bj < 2; ++bj) hv[m][bj] = *(const u32x4*)(hin + (size_t)(row0 + ai * 128 + m * 16) * D + col0 + 128 * bj);
; #pragma unroll
;             for (int m = 0; m < 4; ++m) {
;                 const int r = row0 + ai * 128 + m * 16; float ss = 0.f;
; #pragma unroll
;                 for (int bj = 0; bj < 2; ++bj) {
;                     const u32x4 w0 = hv[m][bj];
;                     f32x4 a = {bflo(w0.x), bfhi(w0.x), bflo(w0.y), bfhi(w0.y)}, b = {bflo(w0.z), bfhi(w0.z), bflo(w0.w), bfhi(w0.w)};
;                     a += acc[ai][bj][m][0] * scale; b += acc[ai][bj][m][1] * scale;
;                     ss += (a.x * a.x + a.y * a.y) + (a.z * a.z + a.w * a.w) + (b.x * b.x + b.y * b.y) + (b.z * b.z + b.w * b.w);
;                     u32x4 w; w.x = pk2(a.x, a.y); w.y = pk2(a.z, a.w); w.z = pk2(b.x, b.y); w.w = pk2(b.z, b.w); *(u32x4*)(hb + (size_t)r * D + col0 + 128 * bj) = w;
;                 }
;                 ss += __shfl_xor(ss, 16); ss += __shfl_xor(ss, 32); if (fq == 0) part_out[(size_t)r * 16 + u.pn * 4 + wc] = ss;
.LBB0_866:
	s_and_b64 vcc, exec, s[26:27]
	s_cbranch_vccz .LBB0_868
	s_barrier
.LBB0_868:
	s_mov_b32 s101, s62
	s_mov_b32 s99, 0
.Lfold_wout_again:
	s_lshl_b32 s8, s78, 8
	v_mov_b32_e32 v0, v234
	s_add_i32 s8, s8, s61
	s_lshl_b32 s54, s62, 2
	v_and_or_b32 v170, v0, 15, s8
	s_lshl_b32 s8, s62, 8
	v_bfe_u32 v116, v0, 4, 2
	s_or_b32 s8, s8, s70
	v_lshl_or_b32 v2, v116, 3, s8
	v_ashrrev_i32_e32 v3, 31, v2
	v_lshlrev_b64 v[182:183], 1, v[2:3]
	v_ashrrev_i32_e32 v171, 31, v170
	v_lshl_add_u64 v[168:169], s[10:11], 0, v[182:183]
	v_lshlrev_b64 v[184:185], 11, v[170:171]
	v_cmp_eq_u32_e32 vcc, 0, v116
	v_lshl_add_u64 v[116:117], v[168:169], 0, v[184:185]
	global_load_dwordx4 v[178:181], v[116:117], off
	global_load_dwordx4 v[188:191], v[116:117], off offset:256
	v_or_b32_e32 v196, 16, v170
	v_ashrrev_i32_e32 v197, 31, v196
	v_or_b32_e32 v176, 32, v170
	v_lshlrev_b64 v[198:199], 11, v[196:197]
	v_ashrrev_i32_e32 v177, 31, v176
	v_or_b32_e32 v172, 48, v170
	v_lshl_add_u64 v[116:117], v[168:169], 0, v[198:199]
	v_lshlrev_b64 v[194:195], 11, v[176:177]
	v_ashrrev_i32_e32 v173, 31, v172
	global_load_dwordx4 v[152:155], v[116:117], off
	global_load_dwordx4 v[140:143], v[116:117], off offset:256
	v_lshl_add_u64 v[116:117], v[168:169], 0, v[194:195]
	v_lshlrev_b64 v[174:175], 11, v[172:173]
	global_load_dwordx4 v[128:131], v[116:117], off
	global_load_dwordx4 v[124:127], v[116:117], off offset:256
	v_lshl_add_u64 v[116:117], v[168:169], 0, v[174:175]
	global_load_dwordx4 v[120:123], v[116:117], off
	s_nop 0
	global_load_dwordx4 v[116:119], v[116:117], off offset:256
	s_ashr_i32 s55, s54, 31
	s_waitcnt vmcnt(0)
	v_lshlrev_b32_e32 v186, 16, v178
	v_and_b32_e32 v187, 0xffff0000, v178
	v_lshlrev_b32_e32 v178, 16, v179
	v_and_b32_e32 v179, 0xffff0000, v179
	v_lshlrev_b32_e32 v192, 16, v180
	v_and_b32_e32 v193, 0xffff0000, v180
	v_lshlrev_b32_e32 v180, 16, v181
	v_and_b32_e32 v181, 0xffff0000, v181
	v_pk_add_f32 v[150:151], v[150:151], v[178:179]
	v_pk_add_f32 v[148:149], v[148:149], v[186:187]
	v_pk_add_f32 v[178:179], v[146:147], v[180:181]
	v_pk_add_f32 v[146:147], v[144:145], v[192:193]
	v_mul_f32_e32 v0, v149, v149
	v_mul_f32_e32 v144, v151, v151
	v_fmac_f32_e32 v0, v148, v148
	v_fmac_f32_e32 v144, v150, v150
	v_add_f32_e32 v0, v0, v144
	v_mul_f32_e32 v144, v147, v147
	v_fmac_f32_e32 v144, v146, v146
	v_add_f32_e32 v0, v144, v0
	v_mul_f32_e32 v144, v179, v179
	v_fmac_f32_e32 v144, v178, v178
	v_add_f32_e32 v0, v144, v0
	v_cvt_pk_bf16_f32 v144, v148, v149
	v_lshl_add_u64 v[148:149], s[10:11], 0, v[184:185]
	v_cvt_pk_bf16_f32 v145, v150, v151
	v_cvt_pk_bf16_f32 v146, v146, v147
	v_cvt_pk_bf16_f32 v147, v178, v179
	v_lshl_add_u64 v[148:149], v[148:149], 0, v[182:183]
	global_store_dwordx4 v[148:149], v[144:147], off
	v_lshlrev_b32_e32 v150, 16, v190
	v_and_b32_e32 v151, 0xffff0000, v190
	v_lshlrev_b32_e32 v144, 16, v188
	v_and_b32_e32 v145, 0xffff0000, v188
	v_lshlrev_b32_e32 v146, 16, v189
	v_and_b32_e32 v147, 0xffff0000, v189
	v_lshlrev_b32_e32 v178, 16, v191
	v_and_b32_e32 v179, 0xffff0000, v191
	v_pk_add_f32 v[138:139], v[138:139], v[146:147]
	v_pk_add_f32 v[136:137], v[136:137], v[144:145]
	v_pk_add_f32 v[144:145], v[134:135], v[178:179]
	v_pk_add_f32 v[134:135], v[132:133], v[150:151]
	v_mul_f32_e32 v132, v137, v137
	v_mul_f32_e32 v133, v139, v139
	v_fmac_f32_e32 v132, v136, v136
	v_fmac_f32_e32 v133, v138, v138
	v_add_f32_e32 v132, v132, v133
	v_mul_f32_e32 v133, v135, v135
	v_fmac_f32_e32 v133, v134, v134
	v_add_f32_e32 v132, v133, v132
	v_mul_f32_e32 v133, v145, v145
	v_fmac_f32_e32 v133, v144, v144
	v_add_f32_e32 v132, v133, v132
	v_add_f32_e32 v146, v0, v132
	v_cvt_pk_bf16_f32 v132, v136, v137
	v_cvt_pk_bf16_f32 v133, v138, v139
	v_cvt_pk_bf16_f32 v134, v134, v135
	v_cvt_pk_bf16_f32 v135, v144, v145
	global_store_dwordx4 v[148:149], v[132:135], off offset:256
	v_xor_b32_e32 v0, 16, v231
	s_nop 0
	v_and_b32_e32 v132, 64, v231
	v_add_u32_e32 v132, 64, v132
	v_cmp_lt_i32_e64 s[8:9], v0, v132
	v_xor_b32_e32 v134, 32, v231
	s_nop 0
	v_cndmask_b32_e64 v0, v231, v0, s[8:9]
	v_lshlrev_b32_e32 v0, 2, v0
	ds_bpermute_b32 v133, v0, v146
	v_cmp_lt_i32_e64 s[8:9], v134, v132
	s_waitcnt lgkmcnt(0)
	v_add_f32_e32 v133, v146, v133
	v_cndmask_b32_e64 v132, v231, v134, s[8:9]
	v_lshlrev_b32_e32 v132, 2, v132
	ds_bpermute_b32 v134, v132, v133
	s_and_saveexec_b64 s[8:9], vcc
	s_cbranch_execz .LBB0_870
	v_lshlrev_b64 v[136:137], 6, v[170:171]
	v_lshl_add_u64 v[136:137], s[16:17], 0, v[136:137]
	v_lshl_add_u64 v[136:137], s[54:55], 2, v[136:137]
	s_lshl_b32 s62, s60, 2
	v_lshl_add_u64 v[136:137], v[136:137], 0, s[62:63]
	s_waitcnt lgkmcnt(0)
	v_add_f32_e32 v133, v133, v134
	global_store_dword v[136:137], v133, off

; __device__ __forceinline__ unsigned pk2(float lo, float hi) { unsigned r; asm("v_cvt_pk_bf16_f32 %0, %1, %2" : "=v"(r) : "v"(lo), "v"(hi)); return r; }
; __device__ __forceinline__ float bflo(unsigned w) { return __uint_as_float(w << 16); }
; __device__ __forceinline__ float bfhi(unsigned w) { return __uint_as_float(w & 0xffff0000u); }
;     __device__ __forceinline__ void operator()(const AccT& acc, const pg8::Unit& u, int ui, int wr, int wc, int fr, int fq) const {
;     ...
;         for (int ai = 0; ai < 2; ++ai) {
;             u32x4 hv[4][2];
; #pragma unroll
;             for (int m = 0; m < 4; ++m)
; #pragma unroll
;                 for (int bj = 0; bj < 2; ++bj) hv[m][bj] = *(const u32x4*)(hin + (size_t)(row0 + ai * 128 + m * 16) * D + col0 + 128 * bj);
; #pragma unroll
;             for (int m = 0; m < 4; ++m) {
;                 const int r = row0 + ai * 128 + m * 16; float ss = 0.f;
; #pragma unroll
;                 for (int bj = 0; bj < 2; ++bj) {
;                     const u32x4 w0 = hv[m][bj];
;                     f32x4 a = {bflo(w0.x), bfhi(w0.x), bflo(w0.y), bfhi(w0.y)}, b = {bflo(w0.z), bfhi(w0.z), bflo(w0.w), bfhi(w0.w)};
;                     a += acc[ai][bj][m][0] * scale; b += acc[ai][bj][m][1] * scale;
;                     ss += (a.x * a.x + a.y * a.y) + (a.z * a.z + a.w * a.w) + (b.x * b.x + b.y * b.y) + (b.z * b.z + b.w * b.w);
;                     u32x4 w; w.x = pk2(a.x, a.y); w.y = pk2(a.z, a.w); w.z = pk2(b.x, b.y); w.w = pk2(b.z, b.w); *(u32x4*)(hb + (size_t)r * D + col0 + 128 * bj) = w;
;                 }
;                 ss += __shfl_xor(ss, 16); ss += __shfl_xor(ss, 32); if (fq == 0) part_out[(size_t)r * 16 + u.pn * 4 + wc] = ss;
;             }
.LBB0_876:
	s_or_b64 exec, exec, s[8:9]
	s_cmp_lg_u32 s99, 0
	s_cbranch_scc1 .Lfold_wout_done
	s_mov_b32 s99, 1
	s_mov_b32 s62, s101
	s_add_i32 s61, s61, 0x80
	s_nop 1
	v_mov_b64_e32 v[148:149], v[64:65]
	v_mov_b64_e32 v[150:151], v[66:67]
	v_mov_b64_e32 v[144:145], v[60:61]
	v_mov_b64_e32 v[146:147], v[62:63]
	v_mov_b64_e32 v[112:113], v[48:49]
	v_mov_b64_e32 v[114:115], v[50:51]
	v_mov_b64_e32 v[108:109], v[44:45]
	v_mov_b64_e32 v[110:111], v[46:47]
	v_mov_b64_e32 v[96:97], v[32:33]
	v_mov_b64_e32 v[98:99], v[34:35]
	v_mov_b64_e32 v[92:93], v[28:29]
	v_mov_b64_e32 v[94:95], v[30:31]
	v_mov_b64_e32 v[80:81], v[16:17]
	v_mov_b64_e32 v[82:83], v[18:19]
	v_mov_b64_e32 v[76:77], v[12:13]
	v_mov_b64_e32 v[78:79], v[14:15]
	v_mov_b64_e32 v[136:137], v[56:57]
	v_mov_b64_e32 v[138:139], v[58:59]
	v_mov_b64_e32 v[132:133], v[52:53]
	v_mov_b64_e32 v[134:135], v[54:55]
	v_mov_b64_e32 v[104:105], v[40:41]
	v_mov_b64_e32 v[106:107], v[42:43]
	v_mov_b64_e32 v[100:101], v[36:37]
	v_mov_b64_e32 v[102:103], v[38:39]
	v_mov_b64_e32 v[88:89], v[24:25]
	v_mov_b64_e32 v[90:91], v[26:27]
	v_mov_b64_e32 v[84:85], v[20:21]
	v_mov_b64_e32 v[86:87], v[22:23]
	v_mov_b64_e32 v[72:73], v[8:9]
	v_mov_b64_e32 v[74:75], v[10:11]
	v_mov_b64_e32 v[68:69], v[4:5]
	v_mov_b64_e32 v[70:71], v[6:7]
	s_branch .Lfold_wout_again
.Lfold_wout_done:
	s_sub_i32 s61, s61, 0x80
